# code placement: s_nop pads so all live MFMA blocks start 8-byte aligned (on saddr version) + dtype comment
# speedup vs baseline: 1.0005x; 1.0005x over previous
.LBB0_271:
	s_ashr_i32 s63, s62, 31
	s_lshl_b64 s[0:1], s[62:63], 20
	s_add_u32 s66, s49, s0
	s_addc_u32 s67, s82, s1
	s_and_b64 s[0:1], s[4:5], exec
	s_cselect_b32 s0, s67, s75
	s_cselect_b32 s1, s66, s74
	s_ashr_i32 s65, s64, 31
	s_lshl_b64 s[68:69], s[64:65], 20
	s_add_u32 s68, s45, s68
	s_addc_u32 s69, s47, s69
	s_and_b64 s[78:79], s[4:5], exec
	s_cselect_b32 s3, s69, s77
	s_cselect_b32 s63, s68, s76
	s_add_u32 s74, s74, 0x80080
	s_addc_u32 s75, s75, 0
	s_add_u32 s65, s76, 0x100
	s_addc_u32 s71, s77, 0
	s_mov_b32 s90, -2
	s_waitcnt vmcnt(0)
	ds_read_b128 v[146:149], v166
	ds_read_b128 v[150:153], v166 offset:1024
	ds_read_b128 v[154:157], v166 offset:2048
	ds_read_b128 v[170:173], v166 offset:3072
	ds_read_b128 v[174:177], v167
	ds_read_b128 v[178:181], v167 offset:1024
	ds_read_b128 v[182:185], v167 offset:2048
	ds_read_b128 v[186:189], v167 offset:3072
	s_add_u32 s76, s74, 0xfff80080
	s_addc_u32 s77, s75, -1
	s_cmp_eq_u32 s90, 28
	s_cselect_b32 s79, s0, s77
	s_cselect_b32 s78, s1, s76
	s_cselect_b32 s77, s3, s71
	s_cselect_b32 s76, s63, s65
	s_add_i32 m0, s31, 0xc000
	ds_read_b128 v[190:193], v168
	ds_read_b128 v[194:197], v168 offset:1024
	ds_read_b128 v[198:201], v168 offset:2048
	ds_read_b128 v[202:205], v168 offset:3072
	ds_read_b128 v[206:209], v168 offset:4096
	ds_read_b128 v[214:217], v168 offset:5120
	ds_read_b128 v[218:221], v168 offset:6144
	ds_read_b128 v[222:225], v168 offset:7168
	global_load_lds_dwordx4 v138, s[74:75]
	s_add_i32 m0, s31, 0xe000
	s_nop 0
	global_load_lds_dwordx4 v140, s[74:75]
	s_waitcnt vmcnt(8)
	s_waitcnt lgkmcnt(0)
	s_setprio 1
	s_barrier
	v_mfma_f32_16x16x32_bf16 v[124:127], v[146:149], v[190:193], 0
	v_mfma_f32_16x16x32_bf16 v[120:123], v[154:157], v[190:193], 0
	v_mfma_f32_16x16x32_bf16 v[108:111], v[146:149], v[198:201], 0
	v_mfma_f32_16x16x32_bf16 v[104:107], v[154:157], v[198:201], 0
	v_mfma_f32_16x16x32_bf16 v[92:95], v[146:149], v[206:209], 0
	v_mfma_f32_16x16x32_bf16 v[88:91], v[154:157], v[206:209], 0
	v_mfma_f32_16x16x32_bf16 v[76:79], v[146:149], v[218:221], 0
	v_mfma_f32_16x16x32_bf16 v[72:75], v[154:157], v[218:221], 0
	v_mfma_f32_16x16x32_bf16 v[124:127], v[150:153], v[194:197], v[124:127]
	v_mfma_f32_16x16x32_bf16 v[120:123], v[170:173], v[194:197], v[120:123]
	v_mfma_f32_16x16x32_bf16 v[108:111], v[150:153], v[202:205], v[108:111]
	v_mfma_f32_16x16x32_bf16 v[104:107], v[170:173], v[202:205], v[104:107]
	v_mfma_f32_16x16x32_bf16 v[92:95], v[150:153], v[214:217], v[92:95]
	v_mfma_f32_16x16x32_bf16 v[88:91], v[170:173], v[214:217], v[88:91]
	v_mfma_f32_16x16x32_bf16 v[76:79], v[150:153], v[222:225], v[76:79]
	v_mfma_f32_16x16x32_bf16 v[72:75], v[170:173], v[222:225], v[72:75]
	s_setprio 0
	s_setprio 1
	v_mfma_f32_16x16x32_bf16 v[116:119], v[174:177], v[190:193], 0
	v_mfma_f32_16x16x32_bf16 v[112:115], v[182:185], v[190:193], 0
	v_mfma_f32_16x16x32_bf16 v[100:103], v[174:177], v[198:201], 0
	v_mfma_f32_16x16x32_bf16 v[96:99], v[182:185], v[198:201], 0
	v_mfma_f32_16x16x32_bf16 v[84:87], v[174:177], v[206:209], 0
	v_mfma_f32_16x16x32_bf16 v[80:83], v[182:185], v[206:209], 0
	v_mfma_f32_16x16x32_bf16 v[68:71], v[174:177], v[218:221], 0
	v_mfma_f32_16x16x32_bf16 v[64:67], v[182:185], v[218:221], 0
	v_mfma_f32_16x16x32_bf16 v[116:119], v[178:181], v[194:197], v[116:119]
	v_mfma_f32_16x16x32_bf16 v[112:115], v[186:189], v[194:197], v[112:115]
	v_mfma_f32_16x16x32_bf16 v[100:103], v[178:181], v[202:205], v[100:103]
	v_mfma_f32_16x16x32_bf16 v[96:99], v[186:189], v[202:205], v[96:99]
	v_mfma_f32_16x16x32_bf16 v[84:87], v[178:181], v[214:217], v[84:87]
	v_mfma_f32_16x16x32_bf16 v[80:83], v[186:189], v[214:217], v[80:83]
	v_mfma_f32_16x16x32_bf16 v[68:71], v[178:181], v[222:225], v[68:71]
	v_mfma_f32_16x16x32_bf16 v[64:67], v[186:189], v[222:225], v[64:67]
	s_setprio 0
	s_barrier
	s_add_i32 s91, s81, s30
	s_add_u32 s98, s76, s34
	s_addc_u32 s99, s77, s35
	s_mov_b32 m0, s91
	ds_read_b128 v[190:193], v168 offset:16384
	ds_read_b128 v[194:197], v168 offset:17408
	ds_read_b128 v[198:201], v168 offset:18432
	ds_read_b128 v[202:205], v168 offset:19456
	ds_read_b128 v[206:209], v168 offset:20480
	ds_read_b128 v[214:217], v168 offset:21504
	ds_read_b128 v[218:221], v168 offset:22528
	ds_read_b128 v[222:225], v168 offset:23552
	global_load_lds_dwordx4 v130, s[76:77]
	s_add_i32 m0, s91, 0x2000
	s_add_u32 s92, s76, 0x80000
	s_addc_u32 s93, s77, 0
	s_add_i32 s91, s83, s30
	global_load_lds_dwordx4 v134, s[76:77]
	s_mov_b32 m0, s91
	s_add_u32 s100, s78, s34
	s_addc_u32 s101, s79, s35
	global_load_lds_dwordx4 v130, s[92:93]
	s_add_i32 m0, s91, 0x2000
	s_nop 0
	global_load_lds_dwordx4 v134, s[92:93]
	s_mov_b32 m0, s31
	s_nop 0
	global_load_lds_dwordx4 v128, s[78:79]
	s_mov_b32 m0, s51
	s_nop 0
	global_load_lds_dwordx4 v132, s[78:79]
	s_waitcnt vmcnt(8)
	s_waitcnt lgkmcnt(0)
	s_setprio 1
	s_barrier
	v_mfma_f32_16x16x32_bf16 v[60:63], v[146:149], v[190:193], 0
	v_mfma_f32_16x16x32_bf16 v[56:59], v[154:157], v[190:193], 0
	v_mfma_f32_16x16x32_bf16 v[44:47], v[146:149], v[198:201], 0
	v_mfma_f32_16x16x32_bf16 v[40:43], v[154:157], v[198:201], 0
	v_mfma_f32_16x16x32_bf16 v[28:31], v[146:149], v[206:209], 0
	v_mfma_f32_16x16x32_bf16 v[24:27], v[154:157], v[206:209], 0
	v_mfma_f32_16x16x32_bf16 v[12:15], v[146:149], v[218:221], 0
	v_mfma_f32_16x16x32_bf16 v[8:11], v[154:157], v[218:221], 0
	v_mfma_f32_16x16x32_bf16 v[60:63], v[150:153], v[194:197], v[60:63]
	v_mfma_f32_16x16x32_bf16 v[56:59], v[170:173], v[194:197], v[56:59]
	v_mfma_f32_16x16x32_bf16 v[44:47], v[150:153], v[202:205], v[44:47]
	v_mfma_f32_16x16x32_bf16 v[40:43], v[170:173], v[202:205], v[40:43]
	v_mfma_f32_16x16x32_bf16 v[28:31], v[150:153], v[214:217], v[28:31]
	v_mfma_f32_16x16x32_bf16 v[24:27], v[170:173], v[214:217], v[24:27]
	v_mfma_f32_16x16x32_bf16 v[12:15], v[150:153], v[222:225], v[12:15]
	v_mfma_f32_16x16x32_bf16 v[8:11], v[170:173], v[222:225], v[8:11]
	s_setprio 0
	s_setprio 1
	v_mfma_f32_16x16x32_bf16 v[52:55], v[174:177], v[190:193], 0
	v_mfma_f32_16x16x32_bf16 v[48:51], v[182:185], v[190:193], 0
	v_mfma_f32_16x16x32_bf16 v[36:39], v[174:177], v[198:201], 0
	v_mfma_f32_16x16x32_bf16 v[32:35], v[182:185], v[198:201], 0
	v_mfma_f32_16x16x32_bf16 v[20:23], v[174:177], v[206:209], 0
	v_mfma_f32_16x16x32_bf16 v[16:19], v[182:185], v[206:209], 0
	v_mfma_f32_16x16x32_bf16 v[4:7], v[174:177], v[218:221], 0
	v_mfma_f32_16x16x32_bf16 v[0:3], v[182:185], v[218:221], 0
	v_mfma_f32_16x16x32_bf16 v[52:55], v[178:181], v[194:197], v[52:55]
	v_mfma_f32_16x16x32_bf16 v[48:51], v[186:189], v[194:197], v[48:51]
	v_mfma_f32_16x16x32_bf16 v[36:39], v[178:181], v[202:205], v[36:39]
	v_mfma_f32_16x16x32_bf16 v[32:35], v[186:189], v[202:205], v[32:35]
	v_mfma_f32_16x16x32_bf16 v[20:23], v[178:181], v[214:217], v[20:23]
	v_mfma_f32_16x16x32_bf16 v[16:19], v[186:189], v[214:217], v[16:19]
	v_mfma_f32_16x16x32_bf16 v[4:7], v[178:181], v[222:225], v[4:7]
	v_mfma_f32_16x16x32_bf16 v[0:3], v[186:189], v[222:225], v[0:3]
	s_setprio 0
	s_barrier
	s_add_i32 s91, 0, 0x18000
	v_add_u32_e32 v136, s91, v162
	s_add_i32 s92, 0, 0x1c000
	ds_read_b128 v[146:149], v136
	ds_read_b128 v[150:153], v136 offset:1024
	ds_read_b128 v[154:157], v136 offset:2048
	ds_read_b128 v[170:173], v136 offset:3072
	v_add_u32_e32 v136, s92, v162
	ds_read_b128 v[174:177], v136
	ds_read_b128 v[178:181], v136 offset:1024
	ds_read_b128 v[182:185], v136 offset:2048
	ds_read_b128 v[186:189], v136 offset:3072
	s_add_u32 s78, s78, 0x80000
	s_addc_u32 s79, s79, 0
	s_mov_b32 m0, s28
	ds_read_b128 v[190:193], v168 offset:32768
	ds_read_b128 v[194:197], v168 offset:33792
	ds_read_b128 v[198:201], v168 offset:34816
	ds_read_b128 v[202:205], v168 offset:35840
	ds_read_b128 v[206:209], v168 offset:36864
	ds_read_b128 v[214:217], v168 offset:37888
	ds_read_b128 v[218:221], v168 offset:38912
	ds_read_b128 v[222:225], v168 offset:39936
	global_load_lds_dwordx4 v128, s[78:79]
	s_mov_b32 m0, s29
	s_nop 0
	global_load_lds_dwordx4 v132, s[78:79]
	s_waitcnt vmcnt(8)
	s_waitcnt lgkmcnt(0)
	s_setprio 1
	s_barrier
	v_mfma_f32_16x16x32_bf16 v[124:127], v[146:149], v[190:193], v[124:127]
	v_mfma_f32_16x16x32_bf16 v[120:123], v[154:157], v[190:193], v[120:123]
	v_mfma_f32_16x16x32_bf16 v[108:111], v[146:149], v[198:201], v[108:111]
	v_mfma_f32_16x16x32_bf16 v[104:107], v[154:157], v[198:201], v[104:107]
	v_mfma_f32_16x16x32_bf16 v[92:95], v[146:149], v[206:209], v[92:95]
	v_mfma_f32_16x16x32_bf16 v[88:91], v[154:157], v[206:209], v[88:91]
	v_mfma_f32_16x16x32_bf16 v[76:79], v[146:149], v[218:221], v[76:79]
	v_mfma_f32_16x16x32_bf16 v[72:75], v[154:157], v[218:221], v[72:75]
	v_mfma_f32_16x16x32_bf16 v[124:127], v[150:153], v[194:197], v[124:127]
	v_mfma_f32_16x16x32_bf16 v[120:123], v[170:173], v[194:197], v[120:123]
	v_mfma_f32_16x16x32_bf16 v[108:111], v[150:153], v[202:205], v[108:111]
	v_mfma_f32_16x16x32_bf16 v[104:107], v[170:173], v[202:205], v[104:107]
	v_mfma_f32_16x16x32_bf16 v[92:95], v[150:153], v[214:217], v[92:95]
	v_mfma_f32_16x16x32_bf16 v[88:91], v[170:173], v[214:217], v[88:91]
	v_mfma_f32_16x16x32_bf16 v[76:79], v[150:153], v[222:225], v[76:79]
	v_mfma_f32_16x16x32_bf16 v[72:75], v[170:173], v[222:225], v[72:75]
	s_setprio 0
	s_setprio 1
	v_mfma_f32_16x16x32_bf16 v[116:119], v[174:177], v[190:193], v[116:119]
	v_mfma_f32_16x16x32_bf16 v[112:115], v[182:185], v[190:193], v[112:115]
	v_mfma_f32_16x16x32_bf16 v[100:103], v[174:177], v[198:201], v[100:103]
	v_mfma_f32_16x16x32_bf16 v[96:99], v[182:185], v[198:201], v[96:99]
	v_mfma_f32_16x16x32_bf16 v[84:87], v[174:177], v[206:209], v[84:87]
	v_mfma_f32_16x16x32_bf16 v[80:83], v[182:185], v[206:209], v[80:83]
	v_mfma_f32_16x16x32_bf16 v[68:71], v[174:177], v[218:221], v[68:71]
	v_mfma_f32_16x16x32_bf16 v[64:67], v[182:185], v[218:221], v[64:67]
	v_mfma_f32_16x16x32_bf16 v[116:119], v[178:181], v[194:197], v[116:119]
	v_mfma_f32_16x16x32_bf16 v[112:115], v[186:189], v[194:197], v[112:115]
	v_mfma_f32_16x16x32_bf16 v[100:103], v[178:181], v[202:205], v[100:103]
	v_mfma_f32_16x16x32_bf16 v[96:99], v[186:189], v[202:205], v[96:99]
	v_mfma_f32_16x16x32_bf16 v[84:87], v[178:181], v[214:217], v[84:87]
	v_mfma_f32_16x16x32_bf16 v[80:83], v[186:189], v[214:217], v[80:83]
	v_mfma_f32_16x16x32_bf16 v[68:71], v[178:181], v[222:225], v[68:71]
	v_mfma_f32_16x16x32_bf16 v[64:67], v[186:189], v[222:225], v[64:67]
	s_setprio 0
	s_barrier
	s_add_i32 s78, s91, s30
	s_mov_b32 m0, s78
	ds_read_b128 v[190:193], v168 offset:49152
	ds_read_b128 v[194:197], v168 offset:50176
	ds_read_b128 v[198:201], v168 offset:51200
	ds_read_b128 v[202:205], v168 offset:52224
	ds_read_b128 v[206:209], v168 offset:53248
	ds_read_b128 v[214:217], v168 offset:54272
	ds_read_b128 v[218:221], v168 offset:55296
	ds_read_b128 v[222:225], v168 offset:56320
	global_load_lds_dwordx4 v130, s[98:99]
	s_add_i32 m0, s78, 0x2000
	s_add_u32 s76, s76, 0x80080
	s_addc_u32 s77, s77, 0
	s_add_i32 s78, s92, s30
	global_load_lds_dwordx4 v134, s[98:99]
	s_mov_b32 m0, s78
	s_nop 0
	global_load_lds_dwordx4 v130, s[76:77]
	s_add_i32 m0, s78, 0x2000
	s_nop 0
	global_load_lds_dwordx4 v134, s[76:77]
	s_mov_b32 m0, s73
	s_nop 0
	global_load_lds_dwordx4 v128, s[100:101]
	s_mov_b32 m0, s80
	s_nop 0
	global_load_lds_dwordx4 v132, s[100:101]
	s_nop 0
	s_waitcnt vmcnt(8)
	s_waitcnt lgkmcnt(0)
	s_setprio 1
	s_barrier
	v_mfma_f32_16x16x32_bf16 v[60:63], v[146:149], v[190:193], v[60:63]
	v_mfma_f32_16x16x32_bf16 v[56:59], v[154:157], v[190:193], v[56:59]
	v_mfma_f32_16x16x32_bf16 v[44:47], v[146:149], v[198:201], v[44:47]
	v_mfma_f32_16x16x32_bf16 v[40:43], v[154:157], v[198:201], v[40:43]
	v_mfma_f32_16x16x32_bf16 v[28:31], v[146:149], v[206:209], v[28:31]
	v_mfma_f32_16x16x32_bf16 v[24:27], v[154:157], v[206:209], v[24:27]
	v_mfma_f32_16x16x32_bf16 v[12:15], v[146:149], v[218:221], v[12:15]
	v_mfma_f32_16x16x32_bf16 v[8:11], v[154:157], v[218:221], v[8:11]
	v_mfma_f32_16x16x32_bf16 v[60:63], v[150:153], v[194:197], v[60:63]
	v_mfma_f32_16x16x32_bf16 v[56:59], v[170:173], v[194:197], v[56:59]
	v_mfma_f32_16x16x32_bf16 v[44:47], v[150:153], v[202:205], v[44:47]
	v_mfma_f32_16x16x32_bf16 v[40:43], v[170:173], v[202:205], v[40:43]
	v_mfma_f32_16x16x32_bf16 v[28:31], v[150:153], v[214:217], v[28:31]
	v_mfma_f32_16x16x32_bf16 v[24:27], v[170:173], v[214:217], v[24:27]
	v_mfma_f32_16x16x32_bf16 v[12:15], v[150:153], v[222:225], v[12:15]
	v_mfma_f32_16x16x32_bf16 v[8:11], v[170:173], v[222:225], v[8:11]
	s_setprio 0
	s_setprio 1
	v_mfma_f32_16x16x32_bf16 v[52:55], v[174:177], v[190:193], v[52:55]
	v_mfma_f32_16x16x32_bf16 v[48:51], v[182:185], v[190:193], v[48:51]
	v_mfma_f32_16x16x32_bf16 v[36:39], v[174:177], v[198:201], v[36:39]
	v_mfma_f32_16x16x32_bf16 v[32:35], v[182:185], v[198:201], v[32:35]
	v_mfma_f32_16x16x32_bf16 v[20:23], v[174:177], v[206:209], v[20:23]
	v_mfma_f32_16x16x32_bf16 v[16:19], v[182:185], v[206:209], v[16:19]
	v_mfma_f32_16x16x32_bf16 v[4:7], v[174:177], v[218:221], v[4:7]
	v_mfma_f32_16x16x32_bf16 v[0:3], v[182:185], v[218:221], v[0:3]
	v_mfma_f32_16x16x32_bf16 v[52:55], v[178:181], v[194:197], v[52:55]
	v_mfma_f32_16x16x32_bf16 v[48:51], v[186:189], v[194:197], v[48:51]
	v_mfma_f32_16x16x32_bf16 v[36:39], v[178:181], v[202:205], v[36:39]
	v_mfma_f32_16x16x32_bf16 v[32:35], v[186:189], v[202:205], v[32:35]
	v_mfma_f32_16x16x32_bf16 v[20:23], v[178:181], v[214:217], v[20:23]
	v_mfma_f32_16x16x32_bf16 v[16:19], v[186:189], v[214:217], v[16:19]
	v_mfma_f32_16x16x32_bf16 v[4:7], v[178:181], v[222:225], v[4:7]
	v_mfma_f32_16x16x32_bf16 v[0:3], v[186:189], v[222:225], v[0:3]
	s_setprio 0
	s_barrier
	s_add_i32 s90, s90, 2
	s_add_u32 s74, s74, 0x100
	s_addc_u32 s75, s75, 0
	s_add_u32 s65, s65, 0x100
	s_addc_u32 s71, s71, 0
	s_cmp_gt_u32 s90, 29
.LBB0_272:
	ds_read_b128 v[146:149], v166
	ds_read_b128 v[150:153], v166 offset:1024
	ds_read_b128 v[154:157], v166 offset:2048
	ds_read_b128 v[170:173], v166 offset:3072
	ds_read_b128 v[174:177], v167
	ds_read_b128 v[178:181], v167 offset:1024
	ds_read_b128 v[182:185], v167 offset:2048
	ds_read_b128 v[186:189], v167 offset:3072
	s_add_u32 s76, s74, 0xfff80080
	s_addc_u32 s77, s75, -1
	s_cmp_eq_u32 s90, 28
	s_cselect_b32 s79, s0, s77
	s_cselect_b32 s78, s1, s76
	s_cselect_b32 s77, s3, s71
	s_cselect_b32 s76, s63, s65
	s_add_i32 m0, s31, 0xc000
	ds_read_b128 v[190:193], v168
	ds_read_b128 v[194:197], v168 offset:1024
	ds_read_b128 v[198:201], v168 offset:2048
	ds_read_b128 v[202:205], v168 offset:3072
	ds_read_b128 v[206:209], v168 offset:4096
	ds_read_b128 v[214:217], v168 offset:5120
	ds_read_b128 v[218:221], v168 offset:6144
	ds_read_b128 v[222:225], v168 offset:7168
	global_load_lds_dwordx4 v138, s[74:75]
	s_add_i32 m0, s31, 0xe000
	s_nop 0
	global_load_lds_dwordx4 v140, s[74:75]
	s_nop 0
	s_waitcnt vmcnt(8)
	s_waitcnt lgkmcnt(0)
	s_setprio 1
	s_barrier
	v_mfma_f32_16x16x32_bf16 v[124:127], v[146:149], v[190:193], v[124:127]
	v_mfma_f32_16x16x32_bf16 v[120:123], v[154:157], v[190:193], v[120:123]
	v_mfma_f32_16x16x32_bf16 v[108:111], v[146:149], v[198:201], v[108:111]
	v_mfma_f32_16x16x32_bf16 v[104:107], v[154:157], v[198:201], v[104:107]
	v_mfma_f32_16x16x32_bf16 v[92:95], v[146:149], v[206:209], v[92:95]
	v_mfma_f32_16x16x32_bf16 v[88:91], v[154:157], v[206:209], v[88:91]
	v_mfma_f32_16x16x32_bf16 v[76:79], v[146:149], v[218:221], v[76:79]
	v_mfma_f32_16x16x32_bf16 v[72:75], v[154:157], v[218:221], v[72:75]
	v_mfma_f32_16x16x32_bf16 v[124:127], v[150:153], v[194:197], v[124:127]
	v_mfma_f32_16x16x32_bf16 v[120:123], v[170:173], v[194:197], v[120:123]
	v_mfma_f32_16x16x32_bf16 v[108:111], v[150:153], v[202:205], v[108:111]
	v_mfma_f32_16x16x32_bf16 v[104:107], v[170:173], v[202:205], v[104:107]
	v_mfma_f32_16x16x32_bf16 v[92:95], v[150:153], v[214:217], v[92:95]
	v_mfma_f32_16x16x32_bf16 v[88:91], v[170:173], v[214:217], v[88:91]
	v_mfma_f32_16x16x32_bf16 v[76:79], v[150:153], v[222:225], v[76:79]
	v_mfma_f32_16x16x32_bf16 v[72:75], v[170:173], v[222:225], v[72:75]
	s_setprio 0
	s_setprio 1
	v_mfma_f32_16x16x32_bf16 v[116:119], v[174:177], v[190:193], v[116:119]
	v_mfma_f32_16x16x32_bf16 v[112:115], v[182:185], v[190:193], v[112:115]
	v_mfma_f32_16x16x32_bf16 v[100:103], v[174:177], v[198:201], v[100:103]
	v_mfma_f32_16x16x32_bf16 v[96:99], v[182:185], v[198:201], v[96:99]
	v_mfma_f32_16x16x32_bf16 v[84:87], v[174:177], v[206:209], v[84:87]
	v_mfma_f32_16x16x32_bf16 v[80:83], v[182:185], v[206:209], v[80:83]
	v_mfma_f32_16x16x32_bf16 v[68:71], v[174:177], v[218:221], v[68:71]
	v_mfma_f32_16x16x32_bf16 v[64:67], v[182:185], v[218:221], v[64:67]
	v_mfma_f32_16x16x32_bf16 v[116:119], v[178:181], v[194:197], v[116:119]
	v_mfma_f32_16x16x32_bf16 v[112:115], v[186:189], v[194:197], v[112:115]
	v_mfma_f32_16x16x32_bf16 v[100:103], v[178:181], v[202:205], v[100:103]
	v_mfma_f32_16x16x32_bf16 v[96:99], v[186:189], v[202:205], v[96:99]
	v_mfma_f32_16x16x32_bf16 v[84:87], v[178:181], v[214:217], v[84:87]
	v_mfma_f32_16x16x32_bf16 v[80:83], v[186:189], v[214:217], v[80:83]
	v_mfma_f32_16x16x32_bf16 v[68:71], v[178:181], v[222:225], v[68:71]
	v_mfma_f32_16x16x32_bf16 v[64:67], v[186:189], v[222:225], v[64:67]
	s_setprio 0
	s_barrier
	s_add_i32 s91, s81, s30
	s_add_u32 s98, s76, s34
	s_addc_u32 s99, s77, s35
	s_mov_b32 m0, s91
	ds_read_b128 v[190:193], v168 offset:16384
	ds_read_b128 v[194:197], v168 offset:17408
	ds_read_b128 v[198:201], v168 offset:18432
	ds_read_b128 v[202:205], v168 offset:19456
	ds_read_b128 v[206:209], v168 offset:20480
	ds_read_b128 v[214:217], v168 offset:21504
	ds_read_b128 v[218:221], v168 offset:22528
	ds_read_b128 v[222:225], v168 offset:23552
	global_load_lds_dwordx4 v130, s[76:77]
	s_add_i32 m0, s91, 0x2000
	s_add_u32 s92, s76, 0x80000
	s_addc_u32 s93, s77, 0
	s_add_i32 s91, s83, s30
	global_load_lds_dwordx4 v134, s[76:77]
	s_mov_b32 m0, s91
	s_add_u32 s100, s78, s34
	s_addc_u32 s101, s79, s35
	global_load_lds_dwordx4 v130, s[92:93]
	s_add_i32 m0, s91, 0x2000
	s_nop 0
	global_load_lds_dwordx4 v134, s[92:93]
	s_mov_b32 m0, s31
	s_nop 0
	global_load_lds_dwordx4 v128, s[78:79]
	s_mov_b32 m0, s51
	s_nop 0
	global_load_lds_dwordx4 v132, s[78:79]
	s_waitcnt vmcnt(8)
	s_waitcnt lgkmcnt(0)
	s_setprio 1
	s_barrier
	v_mfma_f32_16x16x32_bf16 v[60:63], v[146:149], v[190:193], v[60:63]
	v_mfma_f32_16x16x32_bf16 v[56:59], v[154:157], v[190:193], v[56:59]
	v_mfma_f32_16x16x32_bf16 v[44:47], v[146:149], v[198:201], v[44:47]
	v_mfma_f32_16x16x32_bf16 v[40:43], v[154:157], v[198:201], v[40:43]
	v_mfma_f32_16x16x32_bf16 v[28:31], v[146:149], v[206:209], v[28:31]
	v_mfma_f32_16x16x32_bf16 v[24:27], v[154:157], v[206:209], v[24:27]
	v_mfma_f32_16x16x32_bf16 v[12:15], v[146:149], v[218:221], v[12:15]
	v_mfma_f32_16x16x32_bf16 v[8:11], v[154:157], v[218:221], v[8:11]
	v_mfma_f32_16x16x32_bf16 v[60:63], v[150:153], v[194:197], v[60:63]
	v_mfma_f32_16x16x32_bf16 v[56:59], v[170:173], v[194:197], v[56:59]
	v_mfma_f32_16x16x32_bf16 v[44:47], v[150:153], v[202:205], v[44:47]
	v_mfma_f32_16x16x32_bf16 v[40:43], v[170:173], v[202:205], v[40:43]
	v_mfma_f32_16x16x32_bf16 v[28:31], v[150:153], v[214:217], v[28:31]
	v_mfma_f32_16x16x32_bf16 v[24:27], v[170:173], v[214:217], v[24:27]
	v_mfma_f32_16x16x32_bf16 v[12:15], v[150:153], v[222:225], v[12:15]
	v_mfma_f32_16x16x32_bf16 v[8:11], v[170:173], v[222:225], v[8:11]
	s_setprio 0
	s_setprio 1
	v_mfma_f32_16x16x32_bf16 v[52:55], v[174:177], v[190:193], v[52:55]
	v_mfma_f32_16x16x32_bf16 v[48:51], v[182:185], v[190:193], v[48:51]
	v_mfma_f32_16x16x32_bf16 v[36:39], v[174:177], v[198:201], v[36:39]
	v_mfma_f32_16x16x32_bf16 v[32:35], v[182:185], v[198:201], v[32:35]
	v_mfma_f32_16x16x32_bf16 v[20:23], v[174:177], v[206:209], v[20:23]
	v_mfma_f32_16x16x32_bf16 v[16:19], v[182:185], v[206:209], v[16:19]
	v_mfma_f32_16x16x32_bf16 v[4:7], v[174:177], v[218:221], v[4:7]
	v_mfma_f32_16x16x32_bf16 v[0:3], v[182:185], v[218:221], v[0:3]
	v_mfma_f32_16x16x32_bf16 v[52:55], v[178:181], v[194:197], v[52:55]
	v_mfma_f32_16x16x32_bf16 v[48:51], v[186:189], v[194:197], v[48:51]
	v_mfma_f32_16x16x32_bf16 v[36:39], v[178:181], v[202:205], v[36:39]
	v_mfma_f32_16x16x32_bf16 v[32:35], v[186:189], v[202:205], v[32:35]
	v_mfma_f32_16x16x32_bf16 v[20:23], v[178:181], v[214:217], v[20:23]
	v_mfma_f32_16x16x32_bf16 v[16:19], v[186:189], v[214:217], v[16:19]
	v_mfma_f32_16x16x32_bf16 v[4:7], v[178:181], v[222:225], v[4:7]
	v_mfma_f32_16x16x32_bf16 v[0:3], v[186:189], v[222:225], v[0:3]
	s_setprio 0
	s_barrier
	s_add_i32 s91, 0, 0x18000
	v_add_u32_e32 v136, s91, v162
	s_add_i32 s92, 0, 0x1c000
	ds_read_b128 v[146:149], v136
	ds_read_b128 v[150:153], v136 offset:1024
	ds_read_b128 v[154:157], v136 offset:2048
	ds_read_b128 v[170:173], v136 offset:3072
	v_add_u32_e32 v136, s92, v162
	ds_read_b128 v[174:177], v136
	ds_read_b128 v[178:181], v136 offset:1024
	ds_read_b128 v[182:185], v136 offset:2048
	ds_read_b128 v[186:189], v136 offset:3072
	s_add_u32 s78, s78, 0x80000
	s_addc_u32 s79, s79, 0
	s_mov_b32 m0, s28
	ds_read_b128 v[190:193], v168 offset:32768
	ds_read_b128 v[194:197], v168 offset:33792
	ds_read_b128 v[198:201], v168 offset:34816
	ds_read_b128 v[202:205], v168 offset:35840
	ds_read_b128 v[206:209], v168 offset:36864
	ds_read_b128 v[214:217], v168 offset:37888
	ds_read_b128 v[218:221], v168 offset:38912
	ds_read_b128 v[222:225], v168 offset:39936
	global_load_lds_dwordx4 v128, s[78:79]
	s_mov_b32 m0, s29
	s_nop 0
	global_load_lds_dwordx4 v132, s[78:79]
	s_waitcnt vmcnt(8)
	s_waitcnt lgkmcnt(0)
	s_setprio 1
	s_barrier
	v_mfma_f32_16x16x32_bf16 v[124:127], v[146:149], v[190:193], v[124:127]
	v_mfma_f32_16x16x32_bf16 v[120:123], v[154:157], v[190:193], v[120:123]
	v_mfma_f32_16x16x32_bf16 v[108:111], v[146:149], v[198:201], v[108:111]
	v_mfma_f32_16x16x32_bf16 v[104:107], v[154:157], v[198:201], v[104:107]
	v_mfma_f32_16x16x32_bf16 v[92:95], v[146:149], v[206:209], v[92:95]
	v_mfma_f32_16x16x32_bf16 v[88:91], v[154:157], v[206:209], v[88:91]
	v_mfma_f32_16x16x32_bf16 v[76:79], v[146:149], v[218:221], v[76:79]
	v_mfma_f32_16x16x32_bf16 v[72:75], v[154:157], v[218:221], v[72:75]
	v_mfma_f32_16x16x32_bf16 v[124:127], v[150:153], v[194:197], v[124:127]
	v_mfma_f32_16x16x32_bf16 v[120:123], v[170:173], v[194:197], v[120:123]
	v_mfma_f32_16x16x32_bf16 v[108:111], v[150:153], v[202:205], v[108:111]
	v_mfma_f32_16x16x32_bf16 v[104:107], v[170:173], v[202:205], v[104:107]
	v_mfma_f32_16x16x32_bf16 v[92:95], v[150:153], v[214:217], v[92:95]
	v_mfma_f32_16x16x32_bf16 v[88:91], v[170:173], v[214:217], v[88:91]
	v_mfma_f32_16x16x32_bf16 v[76:79], v[150:153], v[222:225], v[76:79]
	v_mfma_f32_16x16x32_bf16 v[72:75], v[170:173], v[222:225], v[72:75]
	s_setprio 0
	s_setprio 1
	v_mfma_f32_16x16x32_bf16 v[116:119], v[174:177], v[190:193], v[116:119]
	v_mfma_f32_16x16x32_bf16 v[112:115], v[182:185], v[190:193], v[112:115]
	v_mfma_f32_16x16x32_bf16 v[100:103], v[174:177], v[198:201], v[100:103]
	v_mfma_f32_16x16x32_bf16 v[96:99], v[182:185], v[198:201], v[96:99]
	v_mfma_f32_16x16x32_bf16 v[84:87], v[174:177], v[206:209], v[84:87]
	v_mfma_f32_16x16x32_bf16 v[80:83], v[182:185], v[206:209], v[80:83]
	v_mfma_f32_16x16x32_bf16 v[68:71], v[174:177], v[218:221], v[68:71]
	v_mfma_f32_16x16x32_bf16 v[64:67], v[182:185], v[218:221], v[64:67]
	v_mfma_f32_16x16x32_bf16 v[116:119], v[178:181], v[194:197], v[116:119]
	v_mfma_f32_16x16x32_bf16 v[112:115], v[186:189], v[194:197], v[112:115]
	v_mfma_f32_16x16x32_bf16 v[100:103], v[178:181], v[202:205], v[100:103]
	v_mfma_f32_16x16x32_bf16 v[96:99], v[186:189], v[202:205], v[96:99]
	v_mfma_f32_16x16x32_bf16 v[84:87], v[178:181], v[214:217], v[84:87]
	v_mfma_f32_16x16x32_bf16 v[80:83], v[186:189], v[214:217], v[80:83]
	v_mfma_f32_16x16x32_bf16 v[68:71], v[178:181], v[222:225], v[68:71]
	v_mfma_f32_16x16x32_bf16 v[64:67], v[186:189], v[222:225], v[64:67]
	s_setprio 0
	s_barrier
	s_add_i32 s78, s91, s30
	s_mov_b32 m0, s78
	ds_read_b128 v[190:193], v168 offset:49152
	ds_read_b128 v[194:197], v168 offset:50176
	ds_read_b128 v[198:201], v168 offset:51200
	ds_read_b128 v[202:205], v168 offset:52224
	ds_read_b128 v[206:209], v168 offset:53248
	ds_read_b128 v[214:217], v168 offset:54272
	ds_read_b128 v[218:221], v168 offset:55296
	ds_read_b128 v[222:225], v168 offset:56320
	global_load_lds_dwordx4 v130, s[98:99]
	s_add_i32 m0, s78, 0x2000
	s_add_u32 s76, s76, 0x80080
	s_addc_u32 s77, s77, 0
	s_add_i32 s78, s92, s30
	global_load_lds_dwordx4 v134, s[98:99]
	s_mov_b32 m0, s78
	s_nop 0
	global_load_lds_dwordx4 v130, s[76:77]
	s_add_i32 m0, s78, 0x2000
	s_nop 0
	global_load_lds_dwordx4 v134, s[76:77]
	s_mov_b32 m0, s73
	s_nop 0
	global_load_lds_dwordx4 v128, s[100:101]
	s_mov_b32 m0, s80
	s_nop 0
	global_load_lds_dwordx4 v132, s[100:101]
	s_nop 0
	s_waitcnt vmcnt(8)
	s_waitcnt lgkmcnt(0)
	s_setprio 1
	s_barrier
	v_mfma_f32_16x16x32_bf16 v[60:63], v[146:149], v[190:193], v[60:63]
	v_mfma_f32_16x16x32_bf16 v[56:59], v[154:157], v[190:193], v[56:59]
	v_mfma_f32_16x16x32_bf16 v[44:47], v[146:149], v[198:201], v[44:47]
	v_mfma_f32_16x16x32_bf16 v[40:43], v[154:157], v[198:201], v[40:43]
	v_mfma_f32_16x16x32_bf16 v[28:31], v[146:149], v[206:209], v[28:31]
	v_mfma_f32_16x16x32_bf16 v[24:27], v[154:157], v[206:209], v[24:27]
	v_mfma_f32_16x16x32_bf16 v[12:15], v[146:149], v[218:221], v[12:15]
	v_mfma_f32_16x16x32_bf16 v[8:11], v[154:157], v[218:221], v[8:11]
	v_mfma_f32_16x16x32_bf16 v[60:63], v[150:153], v[194:197], v[60:63]
	v_mfma_f32_16x16x32_bf16 v[56:59], v[170:173], v[194:197], v[56:59]
	v_mfma_f32_16x16x32_bf16 v[44:47], v[150:153], v[202:205], v[44:47]
	v_mfma_f32_16x16x32_bf16 v[40:43], v[170:173], v[202:205], v[40:43]
	v_mfma_f32_16x16x32_bf16 v[28:31], v[150:153], v[214:217], v[28:31]
	v_mfma_f32_16x16x32_bf16 v[24:27], v[170:173], v[214:217], v[24:27]
	v_mfma_f32_16x16x32_bf16 v[12:15], v[150:153], v[222:225], v[12:15]
	v_mfma_f32_16x16x32_bf16 v[8:11], v[170:173], v[222:225], v[8:11]
	s_setprio 0
	s_setprio 1
	v_mfma_f32_16x16x32_bf16 v[52:55], v[174:177], v[190:193], v[52:55]
	v_mfma_f32_16x16x32_bf16 v[48:51], v[182:185], v[190:193], v[48:51]
	v_mfma_f32_16x16x32_bf16 v[36:39], v[174:177], v[198:201], v[36:39]
	v_mfma_f32_16x16x32_bf16 v[32:35], v[182:185], v[198:201], v[32:35]
	v_mfma_f32_16x16x32_bf16 v[20:23], v[174:177], v[206:209], v[20:23]
	v_mfma_f32_16x16x32_bf16 v[16:19], v[182:185], v[206:209], v[16:19]
	v_mfma_f32_16x16x32_bf16 v[4:7], v[174:177], v[218:221], v[4:7]
	v_mfma_f32_16x16x32_bf16 v[0:3], v[182:185], v[218:221], v[0:3]
	v_mfma_f32_16x16x32_bf16 v[52:55], v[178:181], v[194:197], v[52:55]
	v_mfma_f32_16x16x32_bf16 v[48:51], v[186:189], v[194:197], v[48:51]
	v_mfma_f32_16x16x32_bf16 v[36:39], v[178:181], v[202:205], v[36:39]
	v_mfma_f32_16x16x32_bf16 v[32:35], v[186:189], v[202:205], v[32:35]
	v_mfma_f32_16x16x32_bf16 v[20:23], v[178:181], v[214:217], v[20:23]
	v_mfma_f32_16x16x32_bf16 v[16:19], v[186:189], v[214:217], v[16:19]
	v_mfma_f32_16x16x32_bf16 v[4:7], v[178:181], v[222:225], v[4:7]
	v_mfma_f32_16x16x32_bf16 v[0:3], v[186:189], v[222:225], v[0:3]
	s_setprio 0
	s_barrier
	s_add_i32 s90, s90, 2
	s_add_u32 s74, s74, 0x100
	s_addc_u32 s75, s75, 0
	s_add_u32 s65, s65, 0x100
	s_addc_u32 s71, s71, 0
	s_cmp_gt_u32 s90, 29
	s_cbranch_scc0 .LBB0_272
	s_and_b64 vcc, exec, s[36:37]
	s_cbranch_vccz .LBB0_275
	s_barrier

.LBB0_542:
	s_ashr_i32 s35, s34, 31
	s_lshl_b64 s[0:1], s[34:35], 20
	s_add_u32 s36, s29, s0
	s_addc_u32 s37, s30, s1
	s_and_b64 s[0:1], s[6:7], exec
	s_cselect_b32 s0, s37, s43
	s_cselect_b32 s1, s36, s42
	s_ashr_i32 s25, s24, 31
	s_lshl_b64 s[38:39], s[24:25], 20
	s_add_u32 s38, s27, s38
	s_addc_u32 s39, s28, s39
	s_and_b64 s[46:47], s[6:7], exec
	s_cselect_b32 s3, s39, s45
	s_cselect_b32 s9, s38, s44
	s_add_u32 s42, s42, 0x80080
	s_addc_u32 s43, s43, 0
	s_add_u32 s25, s44, 0x100
	s_addc_u32 s35, s45, 0
	s_mov_b32 s58, -2
	s_waitcnt lgkmcnt(0)
	s_waitcnt vmcnt(0)
	ds_read_b128 v[128:131], v216
	ds_read_b128 v[132:135], v216 offset:1024
	ds_read_b128 v[136:139], v216 offset:2048
	ds_read_b128 v[140:143], v216 offset:3072
	ds_read_b128 v[144:147], v217
	ds_read_b128 v[148:151], v217 offset:1024
	ds_read_b128 v[152:155], v217 offset:2048
	ds_read_b128 v[156:159], v217 offset:3072
	s_add_u32 s44, s42, 0xfff80080
	s_addc_u32 s45, s43, -1
	s_cmp_eq_u32 s58, 28
	s_cselect_b32 s47, s0, s45
	s_cselect_b32 s46, s1, s44
	s_cselect_b32 s45, s3, s35
	s_cselect_b32 s44, s9, s25
	s_add_i32 m0, s41, 0xc000
	ds_read_b128 v[160:163], v218
	ds_read_b128 v[164:167], v218 offset:1024
	ds_read_b128 v[168:171], v218 offset:2048
	ds_read_b128 v[172:175], v218 offset:3072
	ds_read_b128 v[192:195], v218 offset:4096
	ds_read_b128 v[196:199], v218 offset:5120
	ds_read_b128 v[200:203], v218 offset:6144
	ds_read_b128 v[204:207], v218 offset:7168
	global_load_lds_dwordx4 v184, s[42:43]
	s_add_i32 m0, s41, 0xe000
	s_nop 0
	global_load_lds_dwordx4 v186, s[42:43]
	s_waitcnt vmcnt(8)
	s_waitcnt lgkmcnt(0)
	s_setprio 1
	s_barrier
	v_mfma_f32_16x16x32_bf16 v[124:127], v[128:131], v[160:163], 0
	v_mfma_f32_16x16x32_bf16 v[120:123], v[136:139], v[160:163], 0
	v_mfma_f32_16x16x32_bf16 v[108:111], v[128:131], v[168:171], 0
	v_mfma_f32_16x16x32_bf16 v[104:107], v[136:139], v[168:171], 0
	v_mfma_f32_16x16x32_bf16 v[92:95], v[128:131], v[192:195], 0
	v_mfma_f32_16x16x32_bf16 v[88:91], v[136:139], v[192:195], 0
	v_mfma_f32_16x16x32_bf16 v[76:79], v[128:131], v[200:203], 0
	v_mfma_f32_16x16x32_bf16 v[72:75], v[136:139], v[200:203], 0
	v_mfma_f32_16x16x32_bf16 v[124:127], v[132:135], v[164:167], v[124:127]
	v_mfma_f32_16x16x32_bf16 v[120:123], v[140:143], v[164:167], v[120:123]
	v_mfma_f32_16x16x32_bf16 v[108:111], v[132:135], v[172:175], v[108:111]
	v_mfma_f32_16x16x32_bf16 v[104:107], v[140:143], v[172:175], v[104:107]
	v_mfma_f32_16x16x32_bf16 v[92:95], v[132:135], v[196:199], v[92:95]
	v_mfma_f32_16x16x32_bf16 v[88:91], v[140:143], v[196:199], v[88:91]
	v_mfma_f32_16x16x32_bf16 v[76:79], v[132:135], v[204:207], v[76:79]
	v_mfma_f32_16x16x32_bf16 v[72:75], v[140:143], v[204:207], v[72:75]
	s_setprio 0
	s_setprio 1
	v_mfma_f32_16x16x32_bf16 v[116:119], v[144:147], v[160:163], 0
	v_mfma_f32_16x16x32_bf16 v[112:115], v[152:155], v[160:163], 0
	v_mfma_f32_16x16x32_bf16 v[100:103], v[144:147], v[168:171], 0
	v_mfma_f32_16x16x32_bf16 v[96:99], v[152:155], v[168:171], 0
	v_mfma_f32_16x16x32_bf16 v[84:87], v[144:147], v[192:195], 0
	v_mfma_f32_16x16x32_bf16 v[80:83], v[152:155], v[192:195], 0
	v_mfma_f32_16x16x32_bf16 v[68:71], v[144:147], v[200:203], 0
	v_mfma_f32_16x16x32_bf16 v[64:67], v[152:155], v[200:203], 0
	v_mfma_f32_16x16x32_bf16 v[116:119], v[148:151], v[164:167], v[116:119]
	v_mfma_f32_16x16x32_bf16 v[112:115], v[156:159], v[164:167], v[112:115]
	v_mfma_f32_16x16x32_bf16 v[100:103], v[148:151], v[172:175], v[100:103]
	v_mfma_f32_16x16x32_bf16 v[96:99], v[156:159], v[172:175], v[96:99]
	v_mfma_f32_16x16x32_bf16 v[84:87], v[148:151], v[196:199], v[84:87]
	v_mfma_f32_16x16x32_bf16 v[80:83], v[156:159], v[196:199], v[80:83]
	v_mfma_f32_16x16x32_bf16 v[68:71], v[148:151], v[204:207], v[68:71]
	v_mfma_f32_16x16x32_bf16 v[64:67], v[156:159], v[204:207], v[64:67]
	s_setprio 0
	s_barrier
	s_add_i32 s59, s55, s31
	s_add_u32 s98, s44, s20
	s_addc_u32 s99, s45, s21
	s_mov_b32 m0, s59
	ds_read_b128 v[160:163], v218 offset:16384
	ds_read_b128 v[164:167], v218 offset:17408
	ds_read_b128 v[168:171], v218 offset:18432
	ds_read_b128 v[172:175], v218 offset:19456
	ds_read_b128 v[192:195], v218 offset:20480
	ds_read_b128 v[196:199], v218 offset:21504
	ds_read_b128 v[200:203], v218 offset:22528
	ds_read_b128 v[204:207], v218 offset:23552
	global_load_lds_dwordx4 v178, s[44:45]
	s_add_i32 m0, s59, 0x2000
	s_add_u32 s60, s44, 0x80000
	s_addc_u32 s61, s45, 0
	s_add_i32 s59, s56, s31
	global_load_lds_dwordx4 v182, s[44:45]
	s_mov_b32 m0, s59
	s_add_u32 s100, s46, s20
	s_addc_u32 s101, s47, s21
	global_load_lds_dwordx4 v178, s[60:61]
	s_add_i32 m0, s59, 0x2000
	s_nop 0
	global_load_lds_dwordx4 v182, s[60:61]
	s_mov_b32 m0, s41
	s_nop 0
	global_load_lds_dwordx4 v176, s[46:47]
	s_mov_b32 m0, s48
	s_nop 0
	global_load_lds_dwordx4 v180, s[46:47]
	s_waitcnt vmcnt(8)
	s_waitcnt lgkmcnt(0)
	s_setprio 1
	s_barrier
	v_mfma_f32_16x16x32_bf16 v[60:63], v[128:131], v[160:163], 0
	v_mfma_f32_16x16x32_bf16 v[56:59], v[136:139], v[160:163], 0
	v_mfma_f32_16x16x32_bf16 v[44:47], v[128:131], v[168:171], 0
	v_mfma_f32_16x16x32_bf16 v[40:43], v[136:139], v[168:171], 0
	v_mfma_f32_16x16x32_bf16 v[28:31], v[128:131], v[192:195], 0
	v_mfma_f32_16x16x32_bf16 v[24:27], v[136:139], v[192:195], 0
	v_mfma_f32_16x16x32_bf16 v[12:15], v[128:131], v[200:203], 0
	v_mfma_f32_16x16x32_bf16 v[8:11], v[136:139], v[200:203], 0
	v_mfma_f32_16x16x32_bf16 v[60:63], v[132:135], v[164:167], v[60:63]
	v_mfma_f32_16x16x32_bf16 v[56:59], v[140:143], v[164:167], v[56:59]
	v_mfma_f32_16x16x32_bf16 v[44:47], v[132:135], v[172:175], v[44:47]
	v_mfma_f32_16x16x32_bf16 v[40:43], v[140:143], v[172:175], v[40:43]
	v_mfma_f32_16x16x32_bf16 v[28:31], v[132:135], v[196:199], v[28:31]
	v_mfma_f32_16x16x32_bf16 v[24:27], v[140:143], v[196:199], v[24:27]
	v_mfma_f32_16x16x32_bf16 v[12:15], v[132:135], v[204:207], v[12:15]
	v_mfma_f32_16x16x32_bf16 v[8:11], v[140:143], v[204:207], v[8:11]
	s_setprio 0
	s_setprio 1
	v_mfma_f32_16x16x32_bf16 v[52:55], v[144:147], v[160:163], 0
	v_mfma_f32_16x16x32_bf16 v[48:51], v[152:155], v[160:163], 0
	v_mfma_f32_16x16x32_bf16 v[36:39], v[144:147], v[168:171], 0
	v_mfma_f32_16x16x32_bf16 v[32:35], v[152:155], v[168:171], 0
	v_mfma_f32_16x16x32_bf16 v[20:23], v[144:147], v[192:195], 0
	v_mfma_f32_16x16x32_bf16 v[16:19], v[152:155], v[192:195], 0
	v_mfma_f32_16x16x32_bf16 v[4:7], v[144:147], v[200:203], 0
	v_mfma_f32_16x16x32_bf16 v[0:3], v[152:155], v[200:203], 0
	v_mfma_f32_16x16x32_bf16 v[52:55], v[148:151], v[164:167], v[52:55]
	v_mfma_f32_16x16x32_bf16 v[48:51], v[156:159], v[164:167], v[48:51]
	v_mfma_f32_16x16x32_bf16 v[36:39], v[148:151], v[172:175], v[36:39]
	v_mfma_f32_16x16x32_bf16 v[32:35], v[156:159], v[172:175], v[32:35]
	v_mfma_f32_16x16x32_bf16 v[20:23], v[148:151], v[196:199], v[20:23]
	v_mfma_f32_16x16x32_bf16 v[16:19], v[156:159], v[196:199], v[16:19]
	v_mfma_f32_16x16x32_bf16 v[4:7], v[148:151], v[204:207], v[4:7]
	v_mfma_f32_16x16x32_bf16 v[0:3], v[156:159], v[204:207], v[0:3]
	s_setprio 0
	s_barrier
	s_add_i32 s59, 0, 0x18000
	s_add_i32 s60, 0, 0x1c000
	v_add_u32_e32 v140, s59, v214
	v_add_u32_e32 v156, s60, v214
	ds_read_b128 v[128:131], v140
	ds_read_b128 v[132:135], v140 offset:1024
	ds_read_b128 v[136:139], v140 offset:2048
	ds_read_b128 v[140:143], v140 offset:3072
	ds_read_b128 v[144:147], v156
	ds_read_b128 v[148:151], v156 offset:1024
	ds_read_b128 v[152:155], v156 offset:2048
	ds_read_b128 v[156:159], v156 offset:3072
	s_add_u32 s46, s46, 0x80000
	s_addc_u32 s47, s47, 0
	s_mov_b32 m0, s49
	ds_read_b128 v[160:163], v218 offset:32768
	ds_read_b128 v[164:167], v218 offset:33792
	ds_read_b128 v[168:171], v218 offset:34816
	ds_read_b128 v[172:175], v218 offset:35840
	ds_read_b128 v[192:195], v218 offset:36864
	ds_read_b128 v[196:199], v218 offset:37888
	ds_read_b128 v[200:203], v218 offset:38912
	ds_read_b128 v[204:207], v218 offset:39936
	global_load_lds_dwordx4 v176, s[46:47]
	s_mov_b32 m0, s50
	s_nop 0
	global_load_lds_dwordx4 v180, s[46:47]
	s_waitcnt vmcnt(8)
	s_waitcnt lgkmcnt(0)
	s_setprio 1
	s_barrier
	v_mfma_f32_16x16x32_bf16 v[124:127], v[128:131], v[160:163], v[124:127]
	v_mfma_f32_16x16x32_bf16 v[120:123], v[136:139], v[160:163], v[120:123]
	v_mfma_f32_16x16x32_bf16 v[108:111], v[128:131], v[168:171], v[108:111]
	v_mfma_f32_16x16x32_bf16 v[104:107], v[136:139], v[168:171], v[104:107]
	v_mfma_f32_16x16x32_bf16 v[92:95], v[128:131], v[192:195], v[92:95]
	v_mfma_f32_16x16x32_bf16 v[88:91], v[136:139], v[192:195], v[88:91]
	v_mfma_f32_16x16x32_bf16 v[76:79], v[128:131], v[200:203], v[76:79]
	v_mfma_f32_16x16x32_bf16 v[72:75], v[136:139], v[200:203], v[72:75]
	v_mfma_f32_16x16x32_bf16 v[124:127], v[132:135], v[164:167], v[124:127]
	v_mfma_f32_16x16x32_bf16 v[120:123], v[140:143], v[164:167], v[120:123]
	v_mfma_f32_16x16x32_bf16 v[108:111], v[132:135], v[172:175], v[108:111]
	v_mfma_f32_16x16x32_bf16 v[104:107], v[140:143], v[172:175], v[104:107]
	v_mfma_f32_16x16x32_bf16 v[92:95], v[132:135], v[196:199], v[92:95]
	v_mfma_f32_16x16x32_bf16 v[88:91], v[140:143], v[196:199], v[88:91]
	v_mfma_f32_16x16x32_bf16 v[76:79], v[132:135], v[204:207], v[76:79]
	v_mfma_f32_16x16x32_bf16 v[72:75], v[140:143], v[204:207], v[72:75]
	s_setprio 0
	s_setprio 1
	v_mfma_f32_16x16x32_bf16 v[116:119], v[144:147], v[160:163], v[116:119]
	v_mfma_f32_16x16x32_bf16 v[112:115], v[152:155], v[160:163], v[112:115]
	v_mfma_f32_16x16x32_bf16 v[100:103], v[144:147], v[168:171], v[100:103]
	v_mfma_f32_16x16x32_bf16 v[96:99], v[152:155], v[168:171], v[96:99]
	v_mfma_f32_16x16x32_bf16 v[84:87], v[144:147], v[192:195], v[84:87]
	v_mfma_f32_16x16x32_bf16 v[80:83], v[152:155], v[192:195], v[80:83]
	v_mfma_f32_16x16x32_bf16 v[68:71], v[144:147], v[200:203], v[68:71]
	v_mfma_f32_16x16x32_bf16 v[64:67], v[152:155], v[200:203], v[64:67]
	v_mfma_f32_16x16x32_bf16 v[116:119], v[148:151], v[164:167], v[116:119]
	v_mfma_f32_16x16x32_bf16 v[112:115], v[156:159], v[164:167], v[112:115]
	v_mfma_f32_16x16x32_bf16 v[100:103], v[148:151], v[172:175], v[100:103]
	v_mfma_f32_16x16x32_bf16 v[96:99], v[156:159], v[172:175], v[96:99]
	v_mfma_f32_16x16x32_bf16 v[84:87], v[148:151], v[196:199], v[84:87]
	v_mfma_f32_16x16x32_bf16 v[80:83], v[156:159], v[196:199], v[80:83]
	v_mfma_f32_16x16x32_bf16 v[68:71], v[148:151], v[204:207], v[68:71]
	v_mfma_f32_16x16x32_bf16 v[64:67], v[156:159], v[204:207], v[64:67]
	s_setprio 0
	s_barrier
	s_add_i32 s46, s59, s31
	s_mov_b32 m0, s46
	ds_read_b128 v[160:163], v218 offset:49152
	ds_read_b128 v[164:167], v218 offset:50176
	ds_read_b128 v[168:171], v218 offset:51200
	ds_read_b128 v[172:175], v218 offset:52224
	ds_read_b128 v[192:195], v218 offset:53248
	ds_read_b128 v[196:199], v218 offset:54272
	ds_read_b128 v[200:203], v218 offset:55296
	ds_read_b128 v[204:207], v218 offset:56320
	global_load_lds_dwordx4 v178, s[98:99]
	s_add_i32 m0, s46, 0x2000
	s_add_u32 s44, s44, 0x80080
	s_addc_u32 s45, s45, 0
	s_add_i32 s46, s60, s31
	global_load_lds_dwordx4 v182, s[98:99]
	s_mov_b32 m0, s46
	s_nop 0
	global_load_lds_dwordx4 v178, s[44:45]
	s_add_i32 m0, s46, 0x2000
	s_nop 0
	global_load_lds_dwordx4 v182, s[44:45]
	s_mov_b32 m0, s52
	s_nop 0
	global_load_lds_dwordx4 v176, s[100:101]
	s_mov_b32 m0, s53
	s_nop 0
	global_load_lds_dwordx4 v180, s[100:101]
	s_nop 0
	s_waitcnt vmcnt(8)
	s_waitcnt lgkmcnt(0)
	s_setprio 1
	s_barrier
	v_mfma_f32_16x16x32_bf16 v[60:63], v[128:131], v[160:163], v[60:63]
	v_mfma_f32_16x16x32_bf16 v[56:59], v[136:139], v[160:163], v[56:59]
	v_mfma_f32_16x16x32_bf16 v[44:47], v[128:131], v[168:171], v[44:47]
	v_mfma_f32_16x16x32_bf16 v[40:43], v[136:139], v[168:171], v[40:43]
	v_mfma_f32_16x16x32_bf16 v[28:31], v[128:131], v[192:195], v[28:31]
	v_mfma_f32_16x16x32_bf16 v[24:27], v[136:139], v[192:195], v[24:27]
	v_mfma_f32_16x16x32_bf16 v[12:15], v[128:131], v[200:203], v[12:15]
	v_mfma_f32_16x16x32_bf16 v[8:11], v[136:139], v[200:203], v[8:11]
	v_mfma_f32_16x16x32_bf16 v[60:63], v[132:135], v[164:167], v[60:63]
	v_mfma_f32_16x16x32_bf16 v[56:59], v[140:143], v[164:167], v[56:59]
	v_mfma_f32_16x16x32_bf16 v[44:47], v[132:135], v[172:175], v[44:47]
	v_mfma_f32_16x16x32_bf16 v[40:43], v[140:143], v[172:175], v[40:43]
	v_mfma_f32_16x16x32_bf16 v[28:31], v[132:135], v[196:199], v[28:31]
	v_mfma_f32_16x16x32_bf16 v[24:27], v[140:143], v[196:199], v[24:27]
	v_mfma_f32_16x16x32_bf16 v[12:15], v[132:135], v[204:207], v[12:15]
	v_mfma_f32_16x16x32_bf16 v[8:11], v[140:143], v[204:207], v[8:11]
	s_setprio 0
	s_setprio 1
	v_mfma_f32_16x16x32_bf16 v[52:55], v[144:147], v[160:163], v[52:55]
	v_mfma_f32_16x16x32_bf16 v[48:51], v[152:155], v[160:163], v[48:51]
	v_mfma_f32_16x16x32_bf16 v[36:39], v[144:147], v[168:171], v[36:39]
	v_mfma_f32_16x16x32_bf16 v[32:35], v[152:155], v[168:171], v[32:35]
	v_mfma_f32_16x16x32_bf16 v[20:23], v[144:147], v[192:195], v[20:23]
	v_mfma_f32_16x16x32_bf16 v[16:19], v[152:155], v[192:195], v[16:19]
	v_mfma_f32_16x16x32_bf16 v[4:7], v[144:147], v[200:203], v[4:7]
	v_mfma_f32_16x16x32_bf16 v[0:3], v[152:155], v[200:203], v[0:3]
	v_mfma_f32_16x16x32_bf16 v[52:55], v[148:151], v[164:167], v[52:55]
	v_mfma_f32_16x16x32_bf16 v[48:51], v[156:159], v[164:167], v[48:51]
	v_mfma_f32_16x16x32_bf16 v[36:39], v[148:151], v[172:175], v[36:39]
	v_mfma_f32_16x16x32_bf16 v[32:35], v[156:159], v[172:175], v[32:35]
	v_mfma_f32_16x16x32_bf16 v[20:23], v[148:151], v[196:199], v[20:23]
	v_mfma_f32_16x16x32_bf16 v[16:19], v[156:159], v[196:199], v[16:19]
	v_mfma_f32_16x16x32_bf16 v[4:7], v[148:151], v[204:207], v[4:7]
	v_mfma_f32_16x16x32_bf16 v[0:3], v[156:159], v[204:207], v[0:3]
	s_setprio 0
	s_barrier
	s_add_i32 s58, s58, 2
	s_add_u32 s42, s42, 0x100
	s_addc_u32 s43, s43, 0
	s_add_u32 s25, s25, 0x100
	s_addc_u32 s35, s35, 0
	s_cmp_gt_u32 s58, 29
.LBB0_543:
	ds_read_b128 v[128:131], v216
	ds_read_b128 v[132:135], v216 offset:1024
	ds_read_b128 v[136:139], v216 offset:2048
	ds_read_b128 v[140:143], v216 offset:3072
	ds_read_b128 v[144:147], v217
	ds_read_b128 v[148:151], v217 offset:1024
	ds_read_b128 v[152:155], v217 offset:2048
	ds_read_b128 v[156:159], v217 offset:3072
	s_add_u32 s44, s42, 0xfff80080
	s_addc_u32 s45, s43, -1
	s_cmp_eq_u32 s58, 28
	s_cselect_b32 s47, s0, s45
	s_cselect_b32 s46, s1, s44
	s_cselect_b32 s45, s3, s35
	s_cselect_b32 s44, s9, s25
	s_add_i32 m0, s41, 0xc000
	ds_read_b128 v[160:163], v218
	ds_read_b128 v[164:167], v218 offset:1024
	ds_read_b128 v[168:171], v218 offset:2048
	ds_read_b128 v[172:175], v218 offset:3072
	ds_read_b128 v[192:195], v218 offset:4096
	ds_read_b128 v[196:199], v218 offset:5120
	ds_read_b128 v[200:203], v218 offset:6144
	ds_read_b128 v[204:207], v218 offset:7168
	global_load_lds_dwordx4 v184, s[42:43]
	s_add_i32 m0, s41, 0xe000
	s_nop 0
	global_load_lds_dwordx4 v186, s[42:43]
	s_nop 0
	s_waitcnt vmcnt(8)
	s_waitcnt lgkmcnt(0)
	s_setprio 1
	s_barrier
	v_mfma_f32_16x16x32_bf16 v[124:127], v[128:131], v[160:163], v[124:127]
	v_mfma_f32_16x16x32_bf16 v[120:123], v[136:139], v[160:163], v[120:123]
	v_mfma_f32_16x16x32_bf16 v[108:111], v[128:131], v[168:171], v[108:111]
	v_mfma_f32_16x16x32_bf16 v[104:107], v[136:139], v[168:171], v[104:107]
	v_mfma_f32_16x16x32_bf16 v[92:95], v[128:131], v[192:195], v[92:95]
	v_mfma_f32_16x16x32_bf16 v[88:91], v[136:139], v[192:195], v[88:91]
	v_mfma_f32_16x16x32_bf16 v[76:79], v[128:131], v[200:203], v[76:79]
	v_mfma_f32_16x16x32_bf16 v[72:75], v[136:139], v[200:203], v[72:75]
	v_mfma_f32_16x16x32_bf16 v[124:127], v[132:135], v[164:167], v[124:127]
	v_mfma_f32_16x16x32_bf16 v[120:123], v[140:143], v[164:167], v[120:123]
	v_mfma_f32_16x16x32_bf16 v[108:111], v[132:135], v[172:175], v[108:111]
	v_mfma_f32_16x16x32_bf16 v[104:107], v[140:143], v[172:175], v[104:107]
	v_mfma_f32_16x16x32_bf16 v[92:95], v[132:135], v[196:199], v[92:95]
	v_mfma_f32_16x16x32_bf16 v[88:91], v[140:143], v[196:199], v[88:91]
	v_mfma_f32_16x16x32_bf16 v[76:79], v[132:135], v[204:207], v[76:79]
	v_mfma_f32_16x16x32_bf16 v[72:75], v[140:143], v[204:207], v[72:75]
	s_setprio 0
	s_setprio 1
	v_mfma_f32_16x16x32_bf16 v[116:119], v[144:147], v[160:163], v[116:119]
	v_mfma_f32_16x16x32_bf16 v[112:115], v[152:155], v[160:163], v[112:115]
	v_mfma_f32_16x16x32_bf16 v[100:103], v[144:147], v[168:171], v[100:103]
	v_mfma_f32_16x16x32_bf16 v[96:99], v[152:155], v[168:171], v[96:99]
	v_mfma_f32_16x16x32_bf16 v[84:87], v[144:147], v[192:195], v[84:87]
	v_mfma_f32_16x16x32_bf16 v[80:83], v[152:155], v[192:195], v[80:83]
	v_mfma_f32_16x16x32_bf16 v[68:71], v[144:147], v[200:203], v[68:71]
	v_mfma_f32_16x16x32_bf16 v[64:67], v[152:155], v[200:203], v[64:67]
	v_mfma_f32_16x16x32_bf16 v[116:119], v[148:151], v[164:167], v[116:119]
	v_mfma_f32_16x16x32_bf16 v[112:115], v[156:159], v[164:167], v[112:115]
	v_mfma_f32_16x16x32_bf16 v[100:103], v[148:151], v[172:175], v[100:103]
	v_mfma_f32_16x16x32_bf16 v[96:99], v[156:159], v[172:175], v[96:99]
	v_mfma_f32_16x16x32_bf16 v[84:87], v[148:151], v[196:199], v[84:87]
	v_mfma_f32_16x16x32_bf16 v[80:83], v[156:159], v[196:199], v[80:83]
	v_mfma_f32_16x16x32_bf16 v[68:71], v[148:151], v[204:207], v[68:71]
	v_mfma_f32_16x16x32_bf16 v[64:67], v[156:159], v[204:207], v[64:67]
	s_setprio 0
	s_barrier
	s_add_i32 s59, s55, s31
	s_add_u32 s98, s44, s20
	s_addc_u32 s99, s45, s21
	s_mov_b32 m0, s59
	ds_read_b128 v[160:163], v218 offset:16384
	ds_read_b128 v[164:167], v218 offset:17408
	ds_read_b128 v[168:171], v218 offset:18432
	ds_read_b128 v[172:175], v218 offset:19456
	ds_read_b128 v[192:195], v218 offset:20480
	ds_read_b128 v[196:199], v218 offset:21504
	ds_read_b128 v[200:203], v218 offset:22528
	ds_read_b128 v[204:207], v218 offset:23552
	global_load_lds_dwordx4 v178, s[44:45]
	s_add_i32 m0, s59, 0x2000
	s_add_u32 s60, s44, 0x80000
	s_addc_u32 s61, s45, 0
	s_add_i32 s59, s56, s31
	global_load_lds_dwordx4 v182, s[44:45]
	s_mov_b32 m0, s59
	s_add_u32 s100, s46, s20
	s_addc_u32 s101, s47, s21
	global_load_lds_dwordx4 v178, s[60:61]
	s_add_i32 m0, s59, 0x2000
	s_nop 0
	global_load_lds_dwordx4 v182, s[60:61]
	s_mov_b32 m0, s41
	s_nop 0
	global_load_lds_dwordx4 v176, s[46:47]
	s_mov_b32 m0, s48
	s_nop 0
	global_load_lds_dwordx4 v180, s[46:47]
	s_waitcnt vmcnt(8)
	s_waitcnt lgkmcnt(0)
	s_setprio 1
	s_barrier
	v_mfma_f32_16x16x32_bf16 v[60:63], v[128:131], v[160:163], v[60:63]
	v_mfma_f32_16x16x32_bf16 v[56:59], v[136:139], v[160:163], v[56:59]
	v_mfma_f32_16x16x32_bf16 v[44:47], v[128:131], v[168:171], v[44:47]
	v_mfma_f32_16x16x32_bf16 v[40:43], v[136:139], v[168:171], v[40:43]
	v_mfma_f32_16x16x32_bf16 v[28:31], v[128:131], v[192:195], v[28:31]
	v_mfma_f32_16x16x32_bf16 v[24:27], v[136:139], v[192:195], v[24:27]
	v_mfma_f32_16x16x32_bf16 v[12:15], v[128:131], v[200:203], v[12:15]
	v_mfma_f32_16x16x32_bf16 v[8:11], v[136:139], v[200:203], v[8:11]
	v_mfma_f32_16x16x32_bf16 v[60:63], v[132:135], v[164:167], v[60:63]
	v_mfma_f32_16x16x32_bf16 v[56:59], v[140:143], v[164:167], v[56:59]
	v_mfma_f32_16x16x32_bf16 v[44:47], v[132:135], v[172:175], v[44:47]
	v_mfma_f32_16x16x32_bf16 v[40:43], v[140:143], v[172:175], v[40:43]
	v_mfma_f32_16x16x32_bf16 v[28:31], v[132:135], v[196:199], v[28:31]
	v_mfma_f32_16x16x32_bf16 v[24:27], v[140:143], v[196:199], v[24:27]
	v_mfma_f32_16x16x32_bf16 v[12:15], v[132:135], v[204:207], v[12:15]
	v_mfma_f32_16x16x32_bf16 v[8:11], v[140:143], v[204:207], v[8:11]
	s_setprio 0
	s_setprio 1
	v_mfma_f32_16x16x32_bf16 v[52:55], v[144:147], v[160:163], v[52:55]
	v_mfma_f32_16x16x32_bf16 v[48:51], v[152:155], v[160:163], v[48:51]
	v_mfma_f32_16x16x32_bf16 v[36:39], v[144:147], v[168:171], v[36:39]
	v_mfma_f32_16x16x32_bf16 v[32:35], v[152:155], v[168:171], v[32:35]
	v_mfma_f32_16x16x32_bf16 v[20:23], v[144:147], v[192:195], v[20:23]
	v_mfma_f32_16x16x32_bf16 v[16:19], v[152:155], v[192:195], v[16:19]
	v_mfma_f32_16x16x32_bf16 v[4:7], v[144:147], v[200:203], v[4:7]
	v_mfma_f32_16x16x32_bf16 v[0:3], v[152:155], v[200:203], v[0:3]
	v_mfma_f32_16x16x32_bf16 v[52:55], v[148:151], v[164:167], v[52:55]
	v_mfma_f32_16x16x32_bf16 v[48:51], v[156:159], v[164:167], v[48:51]
	v_mfma_f32_16x16x32_bf16 v[36:39], v[148:151], v[172:175], v[36:39]
	v_mfma_f32_16x16x32_bf16 v[32:35], v[156:159], v[172:175], v[32:35]
	v_mfma_f32_16x16x32_bf16 v[20:23], v[148:151], v[196:199], v[20:23]
	v_mfma_f32_16x16x32_bf16 v[16:19], v[156:159], v[196:199], v[16:19]
	v_mfma_f32_16x16x32_bf16 v[4:7], v[148:151], v[204:207], v[4:7]
	v_mfma_f32_16x16x32_bf16 v[0:3], v[156:159], v[204:207], v[0:3]
	s_setprio 0
	s_barrier
	s_add_i32 s59, 0, 0x18000
	s_add_i32 s60, 0, 0x1c000
	v_add_u32_e32 v140, s59, v214
	v_add_u32_e32 v156, s60, v214
	ds_read_b128 v[128:131], v140
	ds_read_b128 v[132:135], v140 offset:1024
	ds_read_b128 v[136:139], v140 offset:2048
	ds_read_b128 v[140:143], v140 offset:3072
	ds_read_b128 v[144:147], v156
	ds_read_b128 v[148:151], v156 offset:1024
	ds_read_b128 v[152:155], v156 offset:2048
	ds_read_b128 v[156:159], v156 offset:3072
	s_add_u32 s46, s46, 0x80000
	s_addc_u32 s47, s47, 0
	s_mov_b32 m0, s49
	ds_read_b128 v[160:163], v218 offset:32768
	ds_read_b128 v[164:167], v218 offset:33792
	ds_read_b128 v[168:171], v218 offset:34816
	ds_read_b128 v[172:175], v218 offset:35840
	ds_read_b128 v[192:195], v218 offset:36864
	ds_read_b128 v[196:199], v218 offset:37888
	ds_read_b128 v[200:203], v218 offset:38912
	ds_read_b128 v[204:207], v218 offset:39936
	global_load_lds_dwordx4 v176, s[46:47]
	s_mov_b32 m0, s50
	s_nop 0
	global_load_lds_dwordx4 v180, s[46:47]
	s_waitcnt vmcnt(8)
	s_waitcnt lgkmcnt(0)
	s_setprio 1
	s_barrier
	v_mfma_f32_16x16x32_bf16 v[124:127], v[128:131], v[160:163], v[124:127]
	v_mfma_f32_16x16x32_bf16 v[120:123], v[136:139], v[160:163], v[120:123]
	v_mfma_f32_16x16x32_bf16 v[108:111], v[128:131], v[168:171], v[108:111]
	v_mfma_f32_16x16x32_bf16 v[104:107], v[136:139], v[168:171], v[104:107]
	v_mfma_f32_16x16x32_bf16 v[92:95], v[128:131], v[192:195], v[92:95]
	v_mfma_f32_16x16x32_bf16 v[88:91], v[136:139], v[192:195], v[88:91]
	v_mfma_f32_16x16x32_bf16 v[76:79], v[128:131], v[200:203], v[76:79]
	v_mfma_f32_16x16x32_bf16 v[72:75], v[136:139], v[200:203], v[72:75]
	v_mfma_f32_16x16x32_bf16 v[124:127], v[132:135], v[164:167], v[124:127]
	v_mfma_f32_16x16x32_bf16 v[120:123], v[140:143], v[164:167], v[120:123]
	v_mfma_f32_16x16x32_bf16 v[108:111], v[132:135], v[172:175], v[108:111]
	v_mfma_f32_16x16x32_bf16 v[104:107], v[140:143], v[172:175], v[104:107]
	v_mfma_f32_16x16x32_bf16 v[92:95], v[132:135], v[196:199], v[92:95]
	v_mfma_f32_16x16x32_bf16 v[88:91], v[140:143], v[196:199], v[88:91]
	v_mfma_f32_16x16x32_bf16 v[76:79], v[132:135], v[204:207], v[76:79]
	v_mfma_f32_16x16x32_bf16 v[72:75], v[140:143], v[204:207], v[72:75]
	s_setprio 0
	s_setprio 1
	v_mfma_f32_16x16x32_bf16 v[116:119], v[144:147], v[160:163], v[116:119]
	v_mfma_f32_16x16x32_bf16 v[112:115], v[152:155], v[160:163], v[112:115]
	v_mfma_f32_16x16x32_bf16 v[100:103], v[144:147], v[168:171], v[100:103]
	v_mfma_f32_16x16x32_bf16 v[96:99], v[152:155], v[168:171], v[96:99]
	v_mfma_f32_16x16x32_bf16 v[84:87], v[144:147], v[192:195], v[84:87]
	v_mfma_f32_16x16x32_bf16 v[80:83], v[152:155], v[192:195], v[80:83]
	v_mfma_f32_16x16x32_bf16 v[68:71], v[144:147], v[200:203], v[68:71]
	v_mfma_f32_16x16x32_bf16 v[64:67], v[152:155], v[200:203], v[64:67]
	v_mfma_f32_16x16x32_bf16 v[116:119], v[148:151], v[164:167], v[116:119]
	v_mfma_f32_16x16x32_bf16 v[112:115], v[156:159], v[164:167], v[112:115]
	v_mfma_f32_16x16x32_bf16 v[100:103], v[148:151], v[172:175], v[100:103]
	v_mfma_f32_16x16x32_bf16 v[96:99], v[156:159], v[172:175], v[96:99]
	v_mfma_f32_16x16x32_bf16 v[84:87], v[148:151], v[196:199], v[84:87]
	v_mfma_f32_16x16x32_bf16 v[80:83], v[156:159], v[196:199], v[80:83]
	v_mfma_f32_16x16x32_bf16 v[68:71], v[148:151], v[204:207], v[68:71]
	v_mfma_f32_16x16x32_bf16 v[64:67], v[156:159], v[204:207], v[64:67]
	s_setprio 0
	s_barrier
	s_add_i32 s46, s59, s31
	s_mov_b32 m0, s46
	ds_read_b128 v[160:163], v218 offset:49152
	ds_read_b128 v[164:167], v218 offset:50176
	ds_read_b128 v[168:171], v218 offset:51200
	ds_read_b128 v[172:175], v218 offset:52224
	ds_read_b128 v[192:195], v218 offset:53248
	ds_read_b128 v[196:199], v218 offset:54272
	ds_read_b128 v[200:203], v218 offset:55296
	ds_read_b128 v[204:207], v218 offset:56320
	global_load_lds_dwordx4 v178, s[98:99]
	s_add_i32 m0, s46, 0x2000
	s_add_u32 s44, s44, 0x80080
	s_addc_u32 s45, s45, 0
	s_add_i32 s46, s60, s31
	global_load_lds_dwordx4 v182, s[98:99]
	s_mov_b32 m0, s46
	s_nop 0
	global_load_lds_dwordx4 v178, s[44:45]
	s_add_i32 m0, s46, 0x2000
	s_nop 0
	global_load_lds_dwordx4 v182, s[44:45]
	s_mov_b32 m0, s52
	s_nop 0
	global_load_lds_dwordx4 v176, s[100:101]
	s_mov_b32 m0, s53
	s_nop 0
	global_load_lds_dwordx4 v180, s[100:101]
	s_nop 0
	s_waitcnt vmcnt(8)
	s_waitcnt lgkmcnt(0)
	s_setprio 1
	s_barrier
	v_mfma_f32_16x16x32_bf16 v[60:63], v[128:131], v[160:163], v[60:63]
	v_mfma_f32_16x16x32_bf16 v[56:59], v[136:139], v[160:163], v[56:59]
	v_mfma_f32_16x16x32_bf16 v[44:47], v[128:131], v[168:171], v[44:47]
	v_mfma_f32_16x16x32_bf16 v[40:43], v[136:139], v[168:171], v[40:43]
	v_mfma_f32_16x16x32_bf16 v[28:31], v[128:131], v[192:195], v[28:31]
	v_mfma_f32_16x16x32_bf16 v[24:27], v[136:139], v[192:195], v[24:27]
	v_mfma_f32_16x16x32_bf16 v[12:15], v[128:131], v[200:203], v[12:15]
	v_mfma_f32_16x16x32_bf16 v[8:11], v[136:139], v[200:203], v[8:11]
	v_mfma_f32_16x16x32_bf16 v[60:63], v[132:135], v[164:167], v[60:63]
	v_mfma_f32_16x16x32_bf16 v[56:59], v[140:143], v[164:167], v[56:59]
	v_mfma_f32_16x16x32_bf16 v[44:47], v[132:135], v[172:175], v[44:47]
	v_mfma_f32_16x16x32_bf16 v[40:43], v[140:143], v[172:175], v[40:43]
	v_mfma_f32_16x16x32_bf16 v[28:31], v[132:135], v[196:199], v[28:31]
	v_mfma_f32_16x16x32_bf16 v[24:27], v[140:143], v[196:199], v[24:27]
	v_mfma_f32_16x16x32_bf16 v[12:15], v[132:135], v[204:207], v[12:15]
	v_mfma_f32_16x16x32_bf16 v[8:11], v[140:143], v[204:207], v[8:11]
	s_setprio 0
	s_setprio 1
	v_mfma_f32_16x16x32_bf16 v[52:55], v[144:147], v[160:163], v[52:55]
	v_mfma_f32_16x16x32_bf16 v[48:51], v[152:155], v[160:163], v[48:51]
	v_mfma_f32_16x16x32_bf16 v[36:39], v[144:147], v[168:171], v[36:39]
	v_mfma_f32_16x16x32_bf16 v[32:35], v[152:155], v[168:171], v[32:35]
	v_mfma_f32_16x16x32_bf16 v[20:23], v[144:147], v[192:195], v[20:23]
	v_mfma_f32_16x16x32_bf16 v[16:19], v[152:155], v[192:195], v[16:19]
	v_mfma_f32_16x16x32_bf16 v[4:7], v[144:147], v[200:203], v[4:7]
	v_mfma_f32_16x16x32_bf16 v[0:3], v[152:155], v[200:203], v[0:3]
	v_mfma_f32_16x16x32_bf16 v[52:55], v[148:151], v[164:167], v[52:55]
	v_mfma_f32_16x16x32_bf16 v[48:51], v[156:159], v[164:167], v[48:51]
	v_mfma_f32_16x16x32_bf16 v[36:39], v[148:151], v[172:175], v[36:39]
	v_mfma_f32_16x16x32_bf16 v[32:35], v[156:159], v[172:175], v[32:35]
	v_mfma_f32_16x16x32_bf16 v[20:23], v[148:151], v[196:199], v[20:23]
	v_mfma_f32_16x16x32_bf16 v[16:19], v[156:159], v[196:199], v[16:19]
	v_mfma_f32_16x16x32_bf16 v[4:7], v[148:151], v[204:207], v[4:7]
	v_mfma_f32_16x16x32_bf16 v[0:3], v[156:159], v[204:207], v[0:3]
	s_setprio 0
	s_barrier
	s_add_i32 s58, s58, 2
	s_add_u32 s42, s42, 0x100
	s_addc_u32 s43, s43, 0
	s_add_u32 s25, s25, 0x100
	s_addc_u32 s35, s35, 0
	s_cmp_gt_u32 s58, 29
	s_cbranch_scc0 .LBB0_543
	s_and_b64 vcc, exec, s[22:23]
	s_cbranch_vccz .LBB0_546
	s_barrier

.LBB0_635:
	s_ashr_i32 s67, s66, 31
	s_lshl_b64 s[12:13], s[66:67], 20
	s_add_u32 s70, s55, s12
	s_addc_u32 s71, s57, s13
	s_and_b64 s[6:7], s[6:7], exec
	s_cselect_b32 s1, s71, s11
	s_cselect_b32 s3, s70, s10
	s_add_u32 s6, s8, 0x80080
	s_addc_u32 s7, s9, 0
	s_add_u32 s12, s10, 0x100
	s_addc_u32 s13, s11, 0
	s_mov_b32 s15, -2
	s_waitcnt vmcnt(0)
	ds_read_b128 v[148:151], v197
	ds_read_b128 v[170:173], v197 offset:1024
	ds_read_b128 v[174:177], v197 offset:2048
	ds_read_b128 v[178:181], v197 offset:3072
	ds_read_b128 v[182:185], v198
	ds_read_b128 v[186:189], v198 offset:1024
	ds_read_b128 v[202:205], v198 offset:2048
	ds_read_b128 v[206:209], v198 offset:3072
	s_add_u32 s8, s6, 0xfff80080
	s_addc_u32 s9, s7, -1
	s_cmp_eq_u32 s15, 28
	s_cselect_b32 s11, s69, s9
	s_cselect_b32 s10, s68, s8
	s_cselect_b32 s9, s1, s13
	s_cselect_b32 s8, s3, s12
	s_add_i32 m0, s72, 0xc000
	ds_read_b128 v[214:217], v199
	ds_read_b128 v[218:221], v199 offset:1024
	ds_read_b128 v[222:225], v199 offset:2048
	ds_read_b128 v[226:229], v199 offset:3072
	ds_read_b128 v[230:233], v199 offset:4096
	ds_read_b128 v[234:237], v199 offset:5120
	ds_read_b128 v[238:241], v199 offset:6144
	ds_read_b128 v[242:245], v199 offset:7168
	global_load_lds_dwordx4 v162, s[6:7]
	s_add_i32 m0, s72, 0xe000
	s_nop 0
	global_load_lds_dwordx4 v164, s[6:7]
	s_nop 0
	s_waitcnt vmcnt(8)
	s_waitcnt lgkmcnt(0)
	s_setprio 1
	s_barrier
	v_mfma_f32_16x16x32_bf16 v[112:115], v[148:151], v[214:217], 0
	v_mfma_f32_16x16x32_bf16 v[80:83], v[174:177], v[214:217], 0
	v_mfma_f32_16x16x32_bf16 v[116:119], v[148:151], v[222:225], 0
	v_mfma_f32_16x16x32_bf16 v[88:91], v[174:177], v[222:225], 0
	v_mfma_f32_16x16x32_bf16 v[124:127], v[148:151], v[230:233], 0
	v_mfma_f32_16x16x32_bf16 v[92:95], v[174:177], v[230:233], 0
	v_mfma_f32_16x16x32_bf16 v[120:123], v[148:151], v[238:241], 0
	v_mfma_f32_16x16x32_bf16 v[84:87], v[174:177], v[238:241], 0
	v_mfma_f32_16x16x32_bf16 v[112:115], v[170:173], v[218:221], v[112:115]
	v_mfma_f32_16x16x32_bf16 v[80:83], v[178:181], v[218:221], v[80:83]
	v_mfma_f32_16x16x32_bf16 v[116:119], v[170:173], v[226:229], v[116:119]
	v_mfma_f32_16x16x32_bf16 v[88:91], v[178:181], v[226:229], v[88:91]
	v_mfma_f32_16x16x32_bf16 v[124:127], v[170:173], v[234:237], v[124:127]
	v_mfma_f32_16x16x32_bf16 v[92:95], v[178:181], v[234:237], v[92:95]
	v_mfma_f32_16x16x32_bf16 v[120:123], v[170:173], v[242:245], v[120:123]
	v_mfma_f32_16x16x32_bf16 v[84:87], v[178:181], v[242:245], v[84:87]
	s_setprio 0
	s_setprio 1
	v_mfma_f32_16x16x32_bf16 v[108:111], v[182:185], v[214:217], 0
	v_mfma_f32_16x16x32_bf16 v[76:79], v[202:205], v[214:217], 0
	v_mfma_f32_16x16x32_bf16 v[104:107], v[182:185], v[222:225], 0
	v_mfma_f32_16x16x32_bf16 v[72:75], v[202:205], v[222:225], 0
	v_mfma_f32_16x16x32_bf16 v[100:103], v[182:185], v[230:233], 0
	v_mfma_f32_16x16x32_bf16 v[68:71], v[202:205], v[230:233], 0
	v_mfma_f32_16x16x32_bf16 v[96:99], v[182:185], v[238:241], 0
	v_mfma_f32_16x16x32_bf16 v[64:67], v[202:205], v[238:241], 0
	v_mfma_f32_16x16x32_bf16 v[108:111], v[186:189], v[218:221], v[108:111]
	v_mfma_f32_16x16x32_bf16 v[76:79], v[206:209], v[218:221], v[76:79]
	v_mfma_f32_16x16x32_bf16 v[104:107], v[186:189], v[226:229], v[104:107]
	v_mfma_f32_16x16x32_bf16 v[72:75], v[206:209], v[226:229], v[72:75]
	v_mfma_f32_16x16x32_bf16 v[100:103], v[186:189], v[234:237], v[100:103]
	v_mfma_f32_16x16x32_bf16 v[68:71], v[206:209], v[234:237], v[68:71]
	v_mfma_f32_16x16x32_bf16 v[96:99], v[186:189], v[242:245], v[96:99]
	v_mfma_f32_16x16x32_bf16 v[64:67], v[206:209], v[242:245], v[64:67]
	s_setprio 0
	s_barrier
	s_add_i32 s16, s94, s63
	s_add_u32 s98, s8, s40
	s_addc_u32 s99, s9, s41
	s_mov_b32 m0, s16
	ds_read_b128 v[214:217], v199 offset:16384
	ds_read_b128 v[218:221], v199 offset:17408
	ds_read_b128 v[222:225], v199 offset:18432
	ds_read_b128 v[226:229], v199 offset:19456
	ds_read_b128 v[230:233], v199 offset:20480
	ds_read_b128 v[234:237], v199 offset:21504
	ds_read_b128 v[238:241], v199 offset:22528
	ds_read_b128 v[242:245], v199 offset:23552
	global_load_lds_dwordx4 v154, s[8:9]
	s_add_i32 m0, s16, 0x2000
	s_add_u32 s16, s8, 0x80000
	s_addc_u32 s17, s9, 0
	s_add_i32 s18, s95, s63
	global_load_lds_dwordx4 v158, s[8:9]
	s_mov_b32 m0, s18
	s_add_u32 s100, s10, s40
	s_addc_u32 s101, s11, s41
	global_load_lds_dwordx4 v154, s[16:17]
	s_add_i32 m0, s18, 0x2000
	s_nop 0
	global_load_lds_dwordx4 v158, s[16:17]
	s_mov_b32 m0, s72
	s_nop 0
	global_load_lds_dwordx4 v152, s[10:11]
	s_mov_b32 m0, s73
	s_nop 0
	global_load_lds_dwordx4 v156, s[10:11]
	s_waitcnt vmcnt(8)
	s_waitcnt lgkmcnt(0)
	s_setprio 1
	s_barrier
	v_mfma_f32_16x16x32_bf16 v[48:51], v[148:151], v[214:217], 0
	v_mfma_f32_16x16x32_bf16 v[16:19], v[174:177], v[214:217], 0
	v_mfma_f32_16x16x32_bf16 v[52:55], v[148:151], v[222:225], 0
	v_mfma_f32_16x16x32_bf16 v[24:27], v[174:177], v[222:225], 0
	v_mfma_f32_16x16x32_bf16 v[60:63], v[148:151], v[230:233], 0
	v_mfma_f32_16x16x32_bf16 v[28:31], v[174:177], v[230:233], 0
	v_mfma_f32_16x16x32_bf16 v[56:59], v[148:151], v[238:241], 0
	v_mfma_f32_16x16x32_bf16 v[20:23], v[174:177], v[238:241], 0
	v_mfma_f32_16x16x32_bf16 v[48:51], v[170:173], v[218:221], v[48:51]
	v_mfma_f32_16x16x32_bf16 v[16:19], v[178:181], v[218:221], v[16:19]
	v_mfma_f32_16x16x32_bf16 v[52:55], v[170:173], v[226:229], v[52:55]
	v_mfma_f32_16x16x32_bf16 v[24:27], v[178:181], v[226:229], v[24:27]
	v_mfma_f32_16x16x32_bf16 v[60:63], v[170:173], v[234:237], v[60:63]
	v_mfma_f32_16x16x32_bf16 v[28:31], v[178:181], v[234:237], v[28:31]
	v_mfma_f32_16x16x32_bf16 v[56:59], v[170:173], v[242:245], v[56:59]
	v_mfma_f32_16x16x32_bf16 v[20:23], v[178:181], v[242:245], v[20:23]
	s_setprio 0
	s_setprio 1
	v_mfma_f32_16x16x32_bf16 v[44:47], v[182:185], v[214:217], 0
	v_mfma_f32_16x16x32_bf16 v[12:15], v[202:205], v[214:217], 0
	v_mfma_f32_16x16x32_bf16 v[40:43], v[182:185], v[222:225], 0
	v_mfma_f32_16x16x32_bf16 v[8:11], v[202:205], v[222:225], 0
	v_mfma_f32_16x16x32_bf16 v[36:39], v[182:185], v[230:233], 0
	v_mfma_f32_16x16x32_bf16 v[4:7], v[202:205], v[230:233], 0
	v_mfma_f32_16x16x32_bf16 v[32:35], v[182:185], v[238:241], 0
	v_mfma_f32_16x16x32_bf16 v[0:3], v[202:205], v[238:241], 0
	v_mfma_f32_16x16x32_bf16 v[44:47], v[186:189], v[218:221], v[44:47]
	v_mfma_f32_16x16x32_bf16 v[12:15], v[206:209], v[218:221], v[12:15]
	v_mfma_f32_16x16x32_bf16 v[40:43], v[186:189], v[226:229], v[40:43]
	v_mfma_f32_16x16x32_bf16 v[8:11], v[206:209], v[226:229], v[8:11]
	v_mfma_f32_16x16x32_bf16 v[36:39], v[186:189], v[234:237], v[36:39]
	v_mfma_f32_16x16x32_bf16 v[4:7], v[206:209], v[234:237], v[4:7]
	v_mfma_f32_16x16x32_bf16 v[32:35], v[186:189], v[242:245], v[32:35]
	v_mfma_f32_16x16x32_bf16 v[0:3], v[206:209], v[242:245], v[0:3]
	s_setprio 0
	s_barrier
	s_add_i32 s16, 0, 0x18000
	s_add_i32 s17, 0, 0x1c000
	v_add_u32_e32 v178, s16, v196
	v_add_u32_e32 v201, s17, v196
	ds_read_b128 v[148:151], v178
	ds_read_b128 v[170:173], v178 offset:1024
	ds_read_b128 v[174:177], v178 offset:2048
	ds_read_b128 v[178:181], v178 offset:3072
	ds_read_b128 v[182:185], v201
	ds_read_b128 v[186:189], v201 offset:1024
	ds_read_b128 v[202:205], v201 offset:2048
	ds_read_b128 v[206:209], v201 offset:3072
	s_add_u32 s10, s10, 0x80000
	s_addc_u32 s11, s11, 0
	s_mov_b32 m0, s74
	ds_read_b128 v[214:217], v199 offset:32768
	ds_read_b128 v[218:221], v199 offset:33792
	ds_read_b128 v[222:225], v199 offset:34816
	ds_read_b128 v[226:229], v199 offset:35840
	ds_read_b128 v[230:233], v199 offset:36864
	ds_read_b128 v[234:237], v199 offset:37888
	ds_read_b128 v[238:241], v199 offset:38912
	ds_read_b128 v[242:245], v199 offset:39936
	global_load_lds_dwordx4 v152, s[10:11]
	s_mov_b32 m0, s75
	s_nop 0
	global_load_lds_dwordx4 v156, s[10:11]
	s_waitcnt vmcnt(8)
	s_waitcnt lgkmcnt(0)
	s_setprio 1
	s_barrier
	v_mfma_f32_16x16x32_bf16 v[112:115], v[148:151], v[214:217], v[112:115]
	v_mfma_f32_16x16x32_bf16 v[80:83], v[174:177], v[214:217], v[80:83]
	v_mfma_f32_16x16x32_bf16 v[116:119], v[148:151], v[222:225], v[116:119]
	v_mfma_f32_16x16x32_bf16 v[88:91], v[174:177], v[222:225], v[88:91]
	v_mfma_f32_16x16x32_bf16 v[124:127], v[148:151], v[230:233], v[124:127]
	v_mfma_f32_16x16x32_bf16 v[92:95], v[174:177], v[230:233], v[92:95]
	v_mfma_f32_16x16x32_bf16 v[120:123], v[148:151], v[238:241], v[120:123]
	v_mfma_f32_16x16x32_bf16 v[84:87], v[174:177], v[238:241], v[84:87]
	v_mfma_f32_16x16x32_bf16 v[112:115], v[170:173], v[218:221], v[112:115]
	v_mfma_f32_16x16x32_bf16 v[80:83], v[178:181], v[218:221], v[80:83]
	v_mfma_f32_16x16x32_bf16 v[116:119], v[170:173], v[226:229], v[116:119]
	v_mfma_f32_16x16x32_bf16 v[88:91], v[178:181], v[226:229], v[88:91]
	v_mfma_f32_16x16x32_bf16 v[124:127], v[170:173], v[234:237], v[124:127]
	v_mfma_f32_16x16x32_bf16 v[92:95], v[178:181], v[234:237], v[92:95]
	v_mfma_f32_16x16x32_bf16 v[120:123], v[170:173], v[242:245], v[120:123]
	v_mfma_f32_16x16x32_bf16 v[84:87], v[178:181], v[242:245], v[84:87]
	s_setprio 0
	s_setprio 1
	v_mfma_f32_16x16x32_bf16 v[108:111], v[182:185], v[214:217], v[108:111]
	v_mfma_f32_16x16x32_bf16 v[76:79], v[202:205], v[214:217], v[76:79]
	v_mfma_f32_16x16x32_bf16 v[104:107], v[182:185], v[222:225], v[104:107]
	v_mfma_f32_16x16x32_bf16 v[72:75], v[202:205], v[222:225], v[72:75]
	v_mfma_f32_16x16x32_bf16 v[100:103], v[182:185], v[230:233], v[100:103]
	v_mfma_f32_16x16x32_bf16 v[68:71], v[202:205], v[230:233], v[68:71]
	v_mfma_f32_16x16x32_bf16 v[96:99], v[182:185], v[238:241], v[96:99]
	v_mfma_f32_16x16x32_bf16 v[64:67], v[202:205], v[238:241], v[64:67]
	v_mfma_f32_16x16x32_bf16 v[108:111], v[186:189], v[218:221], v[108:111]
	v_mfma_f32_16x16x32_bf16 v[76:79], v[206:209], v[218:221], v[76:79]
	v_mfma_f32_16x16x32_bf16 v[104:107], v[186:189], v[226:229], v[104:107]
	v_mfma_f32_16x16x32_bf16 v[72:75], v[206:209], v[226:229], v[72:75]
	v_mfma_f32_16x16x32_bf16 v[100:103], v[186:189], v[234:237], v[100:103]
	v_mfma_f32_16x16x32_bf16 v[68:71], v[206:209], v[234:237], v[68:71]
	v_mfma_f32_16x16x32_bf16 v[96:99], v[186:189], v[242:245], v[96:99]
	v_mfma_f32_16x16x32_bf16 v[64:67], v[206:209], v[242:245], v[64:67]
	s_setprio 0
	s_barrier
	s_add_i32 s10, s16, s63
	s_mov_b32 m0, s10
	ds_read_b128 v[214:217], v199 offset:49152
	ds_read_b128 v[218:221], v199 offset:50176
	ds_read_b128 v[222:225], v199 offset:51200
	ds_read_b128 v[226:229], v199 offset:52224
	ds_read_b128 v[230:233], v199 offset:53248
	ds_read_b128 v[234:237], v199 offset:54272
	ds_read_b128 v[238:241], v199 offset:55296
	ds_read_b128 v[242:245], v199 offset:56320
	global_load_lds_dwordx4 v154, s[98:99]
	s_add_i32 m0, s10, 0x2000
	s_add_u32 s8, s8, 0x80080
	s_addc_u32 s9, s9, 0
	s_add_i32 s10, s17, s63
	global_load_lds_dwordx4 v158, s[98:99]
	s_mov_b32 m0, s10
	s_nop 0
	global_load_lds_dwordx4 v154, s[8:9]
	s_add_i32 m0, s10, 0x2000
	s_nop 0
	global_load_lds_dwordx4 v158, s[8:9]
	s_mov_b32 m0, s82
	s_nop 0
	global_load_lds_dwordx4 v152, s[100:101]
	s_mov_b32 m0, s83
	s_nop 0
	global_load_lds_dwordx4 v156, s[100:101]
	s_nop 0
	s_waitcnt vmcnt(8)
	s_waitcnt lgkmcnt(0)
	s_setprio 1
	s_barrier
	v_mfma_f32_16x16x32_bf16 v[48:51], v[148:151], v[214:217], v[48:51]
	v_mfma_f32_16x16x32_bf16 v[16:19], v[174:177], v[214:217], v[16:19]
	v_mfma_f32_16x16x32_bf16 v[52:55], v[148:151], v[222:225], v[52:55]
	v_mfma_f32_16x16x32_bf16 v[24:27], v[174:177], v[222:225], v[24:27]
	v_mfma_f32_16x16x32_bf16 v[60:63], v[148:151], v[230:233], v[60:63]
	v_mfma_f32_16x16x32_bf16 v[28:31], v[174:177], v[230:233], v[28:31]
	v_mfma_f32_16x16x32_bf16 v[56:59], v[148:151], v[238:241], v[56:59]
	v_mfma_f32_16x16x32_bf16 v[20:23], v[174:177], v[238:241], v[20:23]
	v_mfma_f32_16x16x32_bf16 v[48:51], v[170:173], v[218:221], v[48:51]
	v_mfma_f32_16x16x32_bf16 v[16:19], v[178:181], v[218:221], v[16:19]
	v_mfma_f32_16x16x32_bf16 v[52:55], v[170:173], v[226:229], v[52:55]
	v_mfma_f32_16x16x32_bf16 v[24:27], v[178:181], v[226:229], v[24:27]
	v_mfma_f32_16x16x32_bf16 v[60:63], v[170:173], v[234:237], v[60:63]
	v_mfma_f32_16x16x32_bf16 v[28:31], v[178:181], v[234:237], v[28:31]
	v_mfma_f32_16x16x32_bf16 v[56:59], v[170:173], v[242:245], v[56:59]
	v_mfma_f32_16x16x32_bf16 v[20:23], v[178:181], v[242:245], v[20:23]
	s_setprio 0
	s_setprio 1
	v_mfma_f32_16x16x32_bf16 v[44:47], v[182:185], v[214:217], v[44:47]
	v_mfma_f32_16x16x32_bf16 v[12:15], v[202:205], v[214:217], v[12:15]
	v_mfma_f32_16x16x32_bf16 v[40:43], v[182:185], v[222:225], v[40:43]
	v_mfma_f32_16x16x32_bf16 v[8:11], v[202:205], v[222:225], v[8:11]
	v_mfma_f32_16x16x32_bf16 v[36:39], v[182:185], v[230:233], v[36:39]
	v_mfma_f32_16x16x32_bf16 v[4:7], v[202:205], v[230:233], v[4:7]
	v_mfma_f32_16x16x32_bf16 v[32:35], v[182:185], v[238:241], v[32:35]
	v_mfma_f32_16x16x32_bf16 v[0:3], v[202:205], v[238:241], v[0:3]
	v_mfma_f32_16x16x32_bf16 v[44:47], v[186:189], v[218:221], v[44:47]
	v_mfma_f32_16x16x32_bf16 v[12:15], v[206:209], v[218:221], v[12:15]
	v_mfma_f32_16x16x32_bf16 v[40:43], v[186:189], v[226:229], v[40:43]
	v_mfma_f32_16x16x32_bf16 v[8:11], v[206:209], v[226:229], v[8:11]
	v_mfma_f32_16x16x32_bf16 v[36:39], v[186:189], v[234:237], v[36:39]
	v_mfma_f32_16x16x32_bf16 v[4:7], v[206:209], v[234:237], v[4:7]
	v_mfma_f32_16x16x32_bf16 v[32:35], v[186:189], v[242:245], v[32:35]
	v_mfma_f32_16x16x32_bf16 v[0:3], v[206:209], v[242:245], v[0:3]
	s_setprio 0
	s_barrier
	s_add_i32 s15, s15, 2
	s_add_u32 s6, s6, 0x100
	s_addc_u32 s7, s7, 0
	s_add_u32 s12, s12, 0x100
	s_addc_u32 s13, s13, 0
	s_cmp_gt_u32 s15, 29
.LBB0_636:
	ds_read_b128 v[148:151], v197
	ds_read_b128 v[170:173], v197 offset:1024
	ds_read_b128 v[174:177], v197 offset:2048
	ds_read_b128 v[178:181], v197 offset:3072
	ds_read_b128 v[182:185], v198
	ds_read_b128 v[186:189], v198 offset:1024
	ds_read_b128 v[202:205], v198 offset:2048
	ds_read_b128 v[206:209], v198 offset:3072
	s_add_u32 s8, s6, 0xfff80080
	s_addc_u32 s9, s7, -1
	s_cmp_eq_u32 s15, 28
	s_cselect_b32 s11, s69, s9
	s_cselect_b32 s10, s68, s8
	s_cselect_b32 s9, s1, s13
	s_cselect_b32 s8, s3, s12
	s_add_i32 m0, s72, 0xc000
	ds_read_b128 v[214:217], v199
	ds_read_b128 v[218:221], v199 offset:1024
	ds_read_b128 v[222:225], v199 offset:2048
	ds_read_b128 v[226:229], v199 offset:3072
	ds_read_b128 v[230:233], v199 offset:4096
	ds_read_b128 v[234:237], v199 offset:5120
	ds_read_b128 v[238:241], v199 offset:6144
	ds_read_b128 v[242:245], v199 offset:7168
	global_load_lds_dwordx4 v162, s[6:7]
	s_add_i32 m0, s72, 0xe000
	s_nop 0
	global_load_lds_dwordx4 v164, s[6:7]
	s_nop 0
	s_waitcnt vmcnt(8)
	s_waitcnt lgkmcnt(0)
	s_setprio 1
	s_barrier
	v_mfma_f32_16x16x32_bf16 v[112:115], v[148:151], v[214:217], v[112:115]
	v_mfma_f32_16x16x32_bf16 v[80:83], v[174:177], v[214:217], v[80:83]
	v_mfma_f32_16x16x32_bf16 v[116:119], v[148:151], v[222:225], v[116:119]
	v_mfma_f32_16x16x32_bf16 v[88:91], v[174:177], v[222:225], v[88:91]
	v_mfma_f32_16x16x32_bf16 v[124:127], v[148:151], v[230:233], v[124:127]
	v_mfma_f32_16x16x32_bf16 v[92:95], v[174:177], v[230:233], v[92:95]
	v_mfma_f32_16x16x32_bf16 v[120:123], v[148:151], v[238:241], v[120:123]
	v_mfma_f32_16x16x32_bf16 v[84:87], v[174:177], v[238:241], v[84:87]
	v_mfma_f32_16x16x32_bf16 v[112:115], v[170:173], v[218:221], v[112:115]
	v_mfma_f32_16x16x32_bf16 v[80:83], v[178:181], v[218:221], v[80:83]
	v_mfma_f32_16x16x32_bf16 v[116:119], v[170:173], v[226:229], v[116:119]
	v_mfma_f32_16x16x32_bf16 v[88:91], v[178:181], v[226:229], v[88:91]
	v_mfma_f32_16x16x32_bf16 v[124:127], v[170:173], v[234:237], v[124:127]
	v_mfma_f32_16x16x32_bf16 v[92:95], v[178:181], v[234:237], v[92:95]
	v_mfma_f32_16x16x32_bf16 v[120:123], v[170:173], v[242:245], v[120:123]
	v_mfma_f32_16x16x32_bf16 v[84:87], v[178:181], v[242:245], v[84:87]
	s_setprio 0
	s_setprio 1
	v_mfma_f32_16x16x32_bf16 v[108:111], v[182:185], v[214:217], v[108:111]
	v_mfma_f32_16x16x32_bf16 v[76:79], v[202:205], v[214:217], v[76:79]
	v_mfma_f32_16x16x32_bf16 v[104:107], v[182:185], v[222:225], v[104:107]
	v_mfma_f32_16x16x32_bf16 v[72:75], v[202:205], v[222:225], v[72:75]
	v_mfma_f32_16x16x32_bf16 v[100:103], v[182:185], v[230:233], v[100:103]
	v_mfma_f32_16x16x32_bf16 v[68:71], v[202:205], v[230:233], v[68:71]
	v_mfma_f32_16x16x32_bf16 v[96:99], v[182:185], v[238:241], v[96:99]
	v_mfma_f32_16x16x32_bf16 v[64:67], v[202:205], v[238:241], v[64:67]
	v_mfma_f32_16x16x32_bf16 v[108:111], v[186:189], v[218:221], v[108:111]
	v_mfma_f32_16x16x32_bf16 v[76:79], v[206:209], v[218:221], v[76:79]
	v_mfma_f32_16x16x32_bf16 v[104:107], v[186:189], v[226:229], v[104:107]
	v_mfma_f32_16x16x32_bf16 v[72:75], v[206:209], v[226:229], v[72:75]
	v_mfma_f32_16x16x32_bf16 v[100:103], v[186:189], v[234:237], v[100:103]
	v_mfma_f32_16x16x32_bf16 v[68:71], v[206:209], v[234:237], v[68:71]
	v_mfma_f32_16x16x32_bf16 v[96:99], v[186:189], v[242:245], v[96:99]
	v_mfma_f32_16x16x32_bf16 v[64:67], v[206:209], v[242:245], v[64:67]
	s_setprio 0
	s_barrier
	s_add_i32 s16, s94, s63
	s_add_u32 s98, s8, s40
	s_addc_u32 s99, s9, s41
	s_mov_b32 m0, s16
	ds_read_b128 v[214:217], v199 offset:16384
	ds_read_b128 v[218:221], v199 offset:17408
	ds_read_b128 v[222:225], v199 offset:18432
	ds_read_b128 v[226:229], v199 offset:19456
	ds_read_b128 v[230:233], v199 offset:20480
	ds_read_b128 v[234:237], v199 offset:21504
	ds_read_b128 v[238:241], v199 offset:22528
	ds_read_b128 v[242:245], v199 offset:23552
	global_load_lds_dwordx4 v154, s[8:9]
	s_add_i32 m0, s16, 0x2000
	s_add_u32 s16, s8, 0x80000
	s_addc_u32 s17, s9, 0
	s_add_i32 s18, s95, s63
	global_load_lds_dwordx4 v158, s[8:9]
	s_mov_b32 m0, s18
	s_add_u32 s100, s10, s40
	s_addc_u32 s101, s11, s41
	global_load_lds_dwordx4 v154, s[16:17]
	s_add_i32 m0, s18, 0x2000
	s_nop 0
	global_load_lds_dwordx4 v158, s[16:17]
	s_mov_b32 m0, s72
	s_nop 0
	global_load_lds_dwordx4 v152, s[10:11]
	s_mov_b32 m0, s73
	s_nop 0
	global_load_lds_dwordx4 v156, s[10:11]
	s_waitcnt vmcnt(8)
	s_waitcnt lgkmcnt(0)
	s_setprio 1
	s_barrier
	v_mfma_f32_16x16x32_bf16 v[48:51], v[148:151], v[214:217], v[48:51]
	v_mfma_f32_16x16x32_bf16 v[16:19], v[174:177], v[214:217], v[16:19]
	v_mfma_f32_16x16x32_bf16 v[52:55], v[148:151], v[222:225], v[52:55]
	v_mfma_f32_16x16x32_bf16 v[24:27], v[174:177], v[222:225], v[24:27]
	v_mfma_f32_16x16x32_bf16 v[60:63], v[148:151], v[230:233], v[60:63]
	v_mfma_f32_16x16x32_bf16 v[28:31], v[174:177], v[230:233], v[28:31]
	v_mfma_f32_16x16x32_bf16 v[56:59], v[148:151], v[238:241], v[56:59]
	v_mfma_f32_16x16x32_bf16 v[20:23], v[174:177], v[238:241], v[20:23]
	v_mfma_f32_16x16x32_bf16 v[48:51], v[170:173], v[218:221], v[48:51]
	v_mfma_f32_16x16x32_bf16 v[16:19], v[178:181], v[218:221], v[16:19]
	v_mfma_f32_16x16x32_bf16 v[52:55], v[170:173], v[226:229], v[52:55]
	v_mfma_f32_16x16x32_bf16 v[24:27], v[178:181], v[226:229], v[24:27]
	v_mfma_f32_16x16x32_bf16 v[60:63], v[170:173], v[234:237], v[60:63]
	v_mfma_f32_16x16x32_bf16 v[28:31], v[178:181], v[234:237], v[28:31]
	v_mfma_f32_16x16x32_bf16 v[56:59], v[170:173], v[242:245], v[56:59]
	v_mfma_f32_16x16x32_bf16 v[20:23], v[178:181], v[242:245], v[20:23]
	s_setprio 0
	s_setprio 1
	v_mfma_f32_16x16x32_bf16 v[44:47], v[182:185], v[214:217], v[44:47]
	v_mfma_f32_16x16x32_bf16 v[12:15], v[202:205], v[214:217], v[12:15]
	v_mfma_f32_16x16x32_bf16 v[40:43], v[182:185], v[222:225], v[40:43]
	v_mfma_f32_16x16x32_bf16 v[8:11], v[202:205], v[222:225], v[8:11]
	v_mfma_f32_16x16x32_bf16 v[36:39], v[182:185], v[230:233], v[36:39]
	v_mfma_f32_16x16x32_bf16 v[4:7], v[202:205], v[230:233], v[4:7]
	v_mfma_f32_16x16x32_bf16 v[32:35], v[182:185], v[238:241], v[32:35]
	v_mfma_f32_16x16x32_bf16 v[0:3], v[202:205], v[238:241], v[0:3]
	v_mfma_f32_16x16x32_bf16 v[44:47], v[186:189], v[218:221], v[44:47]
	v_mfma_f32_16x16x32_bf16 v[12:15], v[206:209], v[218:221], v[12:15]
	v_mfma_f32_16x16x32_bf16 v[40:43], v[186:189], v[226:229], v[40:43]
	v_mfma_f32_16x16x32_bf16 v[8:11], v[206:209], v[226:229], v[8:11]
	v_mfma_f32_16x16x32_bf16 v[36:39], v[186:189], v[234:237], v[36:39]
	v_mfma_f32_16x16x32_bf16 v[4:7], v[206:209], v[234:237], v[4:7]
	v_mfma_f32_16x16x32_bf16 v[32:35], v[186:189], v[242:245], v[32:35]
	v_mfma_f32_16x16x32_bf16 v[0:3], v[206:209], v[242:245], v[0:3]
	s_setprio 0
	s_barrier
	s_add_i32 s16, 0, 0x18000
	s_add_i32 s17, 0, 0x1c000
	v_add_u32_e32 v178, s16, v196
	v_add_u32_e32 v201, s17, v196
	ds_read_b128 v[148:151], v178
	ds_read_b128 v[170:173], v178 offset:1024
	ds_read_b128 v[174:177], v178 offset:2048
	ds_read_b128 v[178:181], v178 offset:3072
	ds_read_b128 v[182:185], v201
	ds_read_b128 v[186:189], v201 offset:1024
	ds_read_b128 v[202:205], v201 offset:2048
	ds_read_b128 v[206:209], v201 offset:3072
	s_add_u32 s10, s10, 0x80000
	s_addc_u32 s11, s11, 0
	s_mov_b32 m0, s74
	ds_read_b128 v[214:217], v199 offset:32768
	ds_read_b128 v[218:221], v199 offset:33792
	ds_read_b128 v[222:225], v199 offset:34816
	ds_read_b128 v[226:229], v199 offset:35840
	ds_read_b128 v[230:233], v199 offset:36864
	ds_read_b128 v[234:237], v199 offset:37888
	ds_read_b128 v[238:241], v199 offset:38912
	ds_read_b128 v[242:245], v199 offset:39936
	global_load_lds_dwordx4 v152, s[10:11]
	s_mov_b32 m0, s75
	s_nop 0
	global_load_lds_dwordx4 v156, s[10:11]
	s_waitcnt vmcnt(8)
	s_waitcnt lgkmcnt(0)
	s_setprio 1
	s_barrier
	v_mfma_f32_16x16x32_bf16 v[112:115], v[148:151], v[214:217], v[112:115]
	v_mfma_f32_16x16x32_bf16 v[80:83], v[174:177], v[214:217], v[80:83]
	v_mfma_f32_16x16x32_bf16 v[116:119], v[148:151], v[222:225], v[116:119]
	v_mfma_f32_16x16x32_bf16 v[88:91], v[174:177], v[222:225], v[88:91]
	v_mfma_f32_16x16x32_bf16 v[124:127], v[148:151], v[230:233], v[124:127]
	v_mfma_f32_16x16x32_bf16 v[92:95], v[174:177], v[230:233], v[92:95]
	v_mfma_f32_16x16x32_bf16 v[120:123], v[148:151], v[238:241], v[120:123]
	v_mfma_f32_16x16x32_bf16 v[84:87], v[174:177], v[238:241], v[84:87]
	v_mfma_f32_16x16x32_bf16 v[112:115], v[170:173], v[218:221], v[112:115]
	v_mfma_f32_16x16x32_bf16 v[80:83], v[178:181], v[218:221], v[80:83]
	v_mfma_f32_16x16x32_bf16 v[116:119], v[170:173], v[226:229], v[116:119]
	v_mfma_f32_16x16x32_bf16 v[88:91], v[178:181], v[226:229], v[88:91]
	v_mfma_f32_16x16x32_bf16 v[124:127], v[170:173], v[234:237], v[124:127]
	v_mfma_f32_16x16x32_bf16 v[92:95], v[178:181], v[234:237], v[92:95]
	v_mfma_f32_16x16x32_bf16 v[120:123], v[170:173], v[242:245], v[120:123]
	v_mfma_f32_16x16x32_bf16 v[84:87], v[178:181], v[242:245], v[84:87]
	s_setprio 0
	s_setprio 1
	v_mfma_f32_16x16x32_bf16 v[108:111], v[182:185], v[214:217], v[108:111]
	v_mfma_f32_16x16x32_bf16 v[76:79], v[202:205], v[214:217], v[76:79]
	v_mfma_f32_16x16x32_bf16 v[104:107], v[182:185], v[222:225], v[104:107]
	v_mfma_f32_16x16x32_bf16 v[72:75], v[202:205], v[222:225], v[72:75]
	v_mfma_f32_16x16x32_bf16 v[100:103], v[182:185], v[230:233], v[100:103]
	v_mfma_f32_16x16x32_bf16 v[68:71], v[202:205], v[230:233], v[68:71]
	v_mfma_f32_16x16x32_bf16 v[96:99], v[182:185], v[238:241], v[96:99]
	v_mfma_f32_16x16x32_bf16 v[64:67], v[202:205], v[238:241], v[64:67]
	v_mfma_f32_16x16x32_bf16 v[108:111], v[186:189], v[218:221], v[108:111]
	v_mfma_f32_16x16x32_bf16 v[76:79], v[206:209], v[218:221], v[76:79]
	v_mfma_f32_16x16x32_bf16 v[104:107], v[186:189], v[226:229], v[104:107]
	v_mfma_f32_16x16x32_bf16 v[72:75], v[206:209], v[226:229], v[72:75]
	v_mfma_f32_16x16x32_bf16 v[100:103], v[186:189], v[234:237], v[100:103]
	v_mfma_f32_16x16x32_bf16 v[68:71], v[206:209], v[234:237], v[68:71]
	v_mfma_f32_16x16x32_bf16 v[96:99], v[186:189], v[242:245], v[96:99]
	v_mfma_f32_16x16x32_bf16 v[64:67], v[206:209], v[242:245], v[64:67]
	s_setprio 0
	s_barrier
	s_add_i32 s10, s16, s63
	s_mov_b32 m0, s10
	ds_read_b128 v[214:217], v199 offset:49152
	ds_read_b128 v[218:221], v199 offset:50176
	ds_read_b128 v[222:225], v199 offset:51200
	ds_read_b128 v[226:229], v199 offset:52224
	ds_read_b128 v[230:233], v199 offset:53248
	ds_read_b128 v[234:237], v199 offset:54272
	ds_read_b128 v[238:241], v199 offset:55296
	ds_read_b128 v[242:245], v199 offset:56320
	global_load_lds_dwordx4 v154, s[98:99]
	s_add_i32 m0, s10, 0x2000
	s_add_u32 s8, s8, 0x80080
	s_addc_u32 s9, s9, 0
	s_add_i32 s10, s17, s63
	global_load_lds_dwordx4 v158, s[98:99]
	s_mov_b32 m0, s10
	s_nop 0
	global_load_lds_dwordx4 v154, s[8:9]
	s_add_i32 m0, s10, 0x2000
	s_nop 0
	global_load_lds_dwordx4 v158, s[8:9]
	s_mov_b32 m0, s82
	s_nop 0
	global_load_lds_dwordx4 v152, s[100:101]
	s_mov_b32 m0, s83
	s_nop 0
	global_load_lds_dwordx4 v156, s[100:101]
	s_nop 0
	s_waitcnt vmcnt(8)
	s_waitcnt lgkmcnt(0)
	s_setprio 1
	s_barrier
	v_mfma_f32_16x16x32_bf16 v[48:51], v[148:151], v[214:217], v[48:51]
	v_mfma_f32_16x16x32_bf16 v[16:19], v[174:177], v[214:217], v[16:19]
	v_mfma_f32_16x16x32_bf16 v[52:55], v[148:151], v[222:225], v[52:55]
	v_mfma_f32_16x16x32_bf16 v[24:27], v[174:177], v[222:225], v[24:27]
	v_mfma_f32_16x16x32_bf16 v[60:63], v[148:151], v[230:233], v[60:63]
	v_mfma_f32_16x16x32_bf16 v[28:31], v[174:177], v[230:233], v[28:31]
	v_mfma_f32_16x16x32_bf16 v[56:59], v[148:151], v[238:241], v[56:59]
	v_mfma_f32_16x16x32_bf16 v[20:23], v[174:177], v[238:241], v[20:23]
	v_mfma_f32_16x16x32_bf16 v[48:51], v[170:173], v[218:221], v[48:51]
	v_mfma_f32_16x16x32_bf16 v[16:19], v[178:181], v[218:221], v[16:19]
	v_mfma_f32_16x16x32_bf16 v[52:55], v[170:173], v[226:229], v[52:55]
	v_mfma_f32_16x16x32_bf16 v[24:27], v[178:181], v[226:229], v[24:27]
	v_mfma_f32_16x16x32_bf16 v[60:63], v[170:173], v[234:237], v[60:63]
	v_mfma_f32_16x16x32_bf16 v[28:31], v[178:181], v[234:237], v[28:31]
	v_mfma_f32_16x16x32_bf16 v[56:59], v[170:173], v[242:245], v[56:59]
	v_mfma_f32_16x16x32_bf16 v[20:23], v[178:181], v[242:245], v[20:23]
	s_setprio 0
	s_setprio 1
	v_mfma_f32_16x16x32_bf16 v[44:47], v[182:185], v[214:217], v[44:47]
	v_mfma_f32_16x16x32_bf16 v[12:15], v[202:205], v[214:217], v[12:15]
	v_mfma_f32_16x16x32_bf16 v[40:43], v[182:185], v[222:225], v[40:43]
	v_mfma_f32_16x16x32_bf16 v[8:11], v[202:205], v[222:225], v[8:11]
	v_mfma_f32_16x16x32_bf16 v[36:39], v[182:185], v[230:233], v[36:39]
	v_mfma_f32_16x16x32_bf16 v[4:7], v[202:205], v[230:233], v[4:7]
	v_mfma_f32_16x16x32_bf16 v[32:35], v[182:185], v[238:241], v[32:35]
	v_mfma_f32_16x16x32_bf16 v[0:3], v[202:205], v[238:241], v[0:3]
	v_mfma_f32_16x16x32_bf16 v[44:47], v[186:189], v[218:221], v[44:47]
	v_mfma_f32_16x16x32_bf16 v[12:15], v[206:209], v[218:221], v[12:15]
	v_mfma_f32_16x16x32_bf16 v[40:43], v[186:189], v[226:229], v[40:43]
	v_mfma_f32_16x16x32_bf16 v[8:11], v[206:209], v[226:229], v[8:11]
	v_mfma_f32_16x16x32_bf16 v[36:39], v[186:189], v[234:237], v[36:39]
	v_mfma_f32_16x16x32_bf16 v[4:7], v[206:209], v[234:237], v[4:7]
	v_mfma_f32_16x16x32_bf16 v[32:35], v[186:189], v[242:245], v[32:35]
	v_mfma_f32_16x16x32_bf16 v[0:3], v[206:209], v[242:245], v[0:3]
	s_setprio 0
	s_barrier
	s_add_i32 s15, s15, 2
	s_add_u32 s6, s6, 0x100
	s_addc_u32 s7, s7, 0
	s_add_u32 s12, s12, 0x100
	s_addc_u32 s13, s13, 0
	s_cmp_gt_u32 s15, 29
	s_cbranch_scc0 .LBB0_636
	s_and_b64 vcc, exec, s[42:43]
	s_cbranch_vccz .LBB0_639
	s_barrier

.LBB0_875:
	s_mov_b32 s1, -2
	s_mov_b64 s[4:5], s[22:23]
	ds_read_b128 v[128:131], v188
	ds_read_b128 v[132:135], v188 offset:1024
	ds_read_b128 v[136:139], v188 offset:2048
	ds_read_b128 v[140:143], v188 offset:3072
	ds_read_b128 v[144:147], v189
	ds_read_b128 v[148:151], v189 offset:1024
	ds_read_b128 v[166:169], v189 offset:2048
	ds_read_b128 v[170:173], v189 offset:3072
	s_add_u32 s40, s38, 0x100
	s_addc_u32 s41, s39, 0
	s_cmpk_eq_i32 s1, 0x52
	s_cselect_b32 s45, s37, s41
	s_cselect_b32 s44, s36, s40
	s_cselect_b32 s43, s17, s5
	s_cselect_b32 s42, s16, s4
	s_add_i32 m0, s48, 0xc000
	ds_read_b128 v[174:177], v190
	ds_read_b128 v[178:181], v190 offset:1024
	ds_read_b128 v[194:197], v190 offset:2048
	ds_read_b128 v[198:201], v190 offset:3072
	ds_read_b128 v[202:205], v190 offset:4096
	ds_read_b128 v[206:209], v190 offset:5120
	ds_read_b128 v[210:213], v190 offset:6144
	ds_read_b128 v[214:217], v190 offset:7168
	global_load_lds_dwordx4 v160, s[38:39]
	s_add_i32 m0, s48, 0xe000
	s_nop 0
	global_load_lds_dwordx4 v162, s[38:39]
	s_nop 0
	s_waitcnt vmcnt(8)
	s_waitcnt lgkmcnt(0)
	s_setprio 1
	s_barrier
	v_mfma_f32_16x16x32_bf16 v[124:127], v[128:131], v[174:177], 0
	v_mfma_f32_16x16x32_bf16 v[120:123], v[136:139], v[174:177], 0
	v_mfma_f32_16x16x32_bf16 v[108:111], v[128:131], v[194:197], 0
	v_mfma_f32_16x16x32_bf16 v[104:107], v[136:139], v[194:197], 0
	v_mfma_f32_16x16x32_bf16 v[92:95], v[128:131], v[202:205], 0
	v_mfma_f32_16x16x32_bf16 v[88:91], v[136:139], v[202:205], 0
	v_mfma_f32_16x16x32_bf16 v[76:79], v[128:131], v[210:213], 0
	v_mfma_f32_16x16x32_bf16 v[72:75], v[136:139], v[210:213], 0
	v_mfma_f32_16x16x32_bf16 v[124:127], v[132:135], v[178:181], v[124:127]
	v_mfma_f32_16x16x32_bf16 v[120:123], v[140:143], v[178:181], v[120:123]
	v_mfma_f32_16x16x32_bf16 v[108:111], v[132:135], v[198:201], v[108:111]
	v_mfma_f32_16x16x32_bf16 v[104:107], v[140:143], v[198:201], v[104:107]
	v_mfma_f32_16x16x32_bf16 v[92:95], v[132:135], v[206:209], v[92:95]
	v_mfma_f32_16x16x32_bf16 v[88:91], v[140:143], v[206:209], v[88:91]
	v_mfma_f32_16x16x32_bf16 v[76:79], v[132:135], v[214:217], v[76:79]
	v_mfma_f32_16x16x32_bf16 v[72:75], v[140:143], v[214:217], v[72:75]
	s_setprio 0
	s_setprio 1
	v_mfma_f32_16x16x32_bf16 v[116:119], v[144:147], v[174:177], 0
	v_mfma_f32_16x16x32_bf16 v[112:115], v[166:169], v[174:177], 0
	v_mfma_f32_16x16x32_bf16 v[100:103], v[144:147], v[194:197], 0
	v_mfma_f32_16x16x32_bf16 v[96:99], v[166:169], v[194:197], 0
	v_mfma_f32_16x16x32_bf16 v[84:87], v[144:147], v[202:205], 0
	v_mfma_f32_16x16x32_bf16 v[80:83], v[166:169], v[202:205], 0
	v_mfma_f32_16x16x32_bf16 v[68:71], v[144:147], v[210:213], 0
	v_mfma_f32_16x16x32_bf16 v[64:67], v[166:169], v[210:213], 0
	v_mfma_f32_16x16x32_bf16 v[116:119], v[148:151], v[178:181], v[116:119]
	v_mfma_f32_16x16x32_bf16 v[112:115], v[170:173], v[178:181], v[112:115]
	v_mfma_f32_16x16x32_bf16 v[100:103], v[148:151], v[198:201], v[100:103]
	v_mfma_f32_16x16x32_bf16 v[96:99], v[170:173], v[198:201], v[96:99]
	v_mfma_f32_16x16x32_bf16 v[84:87], v[148:151], v[206:209], v[84:87]
	v_mfma_f32_16x16x32_bf16 v[80:83], v[170:173], v[206:209], v[80:83]
	v_mfma_f32_16x16x32_bf16 v[68:71], v[148:151], v[214:217], v[68:71]
	v_mfma_f32_16x16x32_bf16 v[64:67], v[170:173], v[214:217], v[64:67]
	s_setprio 0
	s_barrier
	s_add_i32 s3, s70, s33
	s_add_u32 s98, s42, s24
	s_addc_u32 s99, s43, s25
	s_mov_b32 m0, s3
	ds_read_b128 v[174:177], v190 offset:16384
	ds_read_b128 v[178:181], v190 offset:17408
	ds_read_b128 v[194:197], v190 offset:18432
	ds_read_b128 v[198:201], v190 offset:19456
	ds_read_b128 v[202:205], v190 offset:20480
	ds_read_b128 v[206:209], v190 offset:21504
	ds_read_b128 v[210:213], v190 offset:22528
	ds_read_b128 v[214:217], v190 offset:23552
	global_load_lds_dwordx4 v154, s[42:43]
	s_add_i32 m0, s3, 0x2000
	s_add_u32 s38, s42, 0x158000
	s_addc_u32 s39, s43, 0
	s_add_i32 s3, s71, s33
	global_load_lds_dwordx4 v158, s[42:43]
	s_mov_b32 m0, s3
	s_add_u32 s100, s44, s24
	s_addc_u32 s101, s45, s25
	global_load_lds_dwordx4 v154, s[38:39]
	s_add_i32 m0, s3, 0x2000
	s_nop 0
	global_load_lds_dwordx4 v158, s[38:39]
	s_mov_b32 m0, s48
	s_nop 0
	global_load_lds_dwordx4 v152, s[44:45]
	s_mov_b32 m0, s49
	s_nop 0
	global_load_lds_dwordx4 v156, s[44:45]
	s_waitcnt vmcnt(8)
	s_waitcnt lgkmcnt(0)
	s_setprio 1
	s_barrier
	v_mfma_f32_16x16x32_bf16 v[60:63], v[128:131], v[174:177], 0
	v_mfma_f32_16x16x32_bf16 v[56:59], v[136:139], v[174:177], 0
	v_mfma_f32_16x16x32_bf16 v[44:47], v[128:131], v[194:197], 0
	v_mfma_f32_16x16x32_bf16 v[40:43], v[136:139], v[194:197], 0
	v_mfma_f32_16x16x32_bf16 v[28:31], v[128:131], v[202:205], 0
	v_mfma_f32_16x16x32_bf16 v[24:27], v[136:139], v[202:205], 0
	v_mfma_f32_16x16x32_bf16 v[12:15], v[128:131], v[210:213], 0
	v_mfma_f32_16x16x32_bf16 v[8:11], v[136:139], v[210:213], 0
	v_mfma_f32_16x16x32_bf16 v[60:63], v[132:135], v[178:181], v[60:63]
	v_mfma_f32_16x16x32_bf16 v[56:59], v[140:143], v[178:181], v[56:59]
	v_mfma_f32_16x16x32_bf16 v[44:47], v[132:135], v[198:201], v[44:47]
	v_mfma_f32_16x16x32_bf16 v[40:43], v[140:143], v[198:201], v[40:43]
	v_mfma_f32_16x16x32_bf16 v[28:31], v[132:135], v[206:209], v[28:31]
	v_mfma_f32_16x16x32_bf16 v[24:27], v[140:143], v[206:209], v[24:27]
	v_mfma_f32_16x16x32_bf16 v[12:15], v[132:135], v[214:217], v[12:15]
	v_mfma_f32_16x16x32_bf16 v[8:11], v[140:143], v[214:217], v[8:11]
	s_setprio 0
	s_setprio 1
	v_mfma_f32_16x16x32_bf16 v[52:55], v[144:147], v[174:177], 0
	v_mfma_f32_16x16x32_bf16 v[48:51], v[166:169], v[174:177], 0
	v_mfma_f32_16x16x32_bf16 v[36:39], v[144:147], v[194:197], 0
	v_mfma_f32_16x16x32_bf16 v[32:35], v[166:169], v[194:197], 0
	v_mfma_f32_16x16x32_bf16 v[20:23], v[144:147], v[202:205], 0
	v_mfma_f32_16x16x32_bf16 v[16:19], v[166:169], v[202:205], 0
	v_mfma_f32_16x16x32_bf16 v[4:7], v[144:147], v[210:213], 0
	v_mfma_f32_16x16x32_bf16 v[0:3], v[166:169], v[210:213], 0
	v_mfma_f32_16x16x32_bf16 v[52:55], v[148:151], v[178:181], v[52:55]
	v_mfma_f32_16x16x32_bf16 v[48:51], v[170:173], v[178:181], v[48:51]
	v_mfma_f32_16x16x32_bf16 v[36:39], v[148:151], v[198:201], v[36:39]
	v_mfma_f32_16x16x32_bf16 v[32:35], v[170:173], v[198:201], v[32:35]
	v_mfma_f32_16x16x32_bf16 v[20:23], v[148:151], v[206:209], v[20:23]
	v_mfma_f32_16x16x32_bf16 v[16:19], v[170:173], v[206:209], v[16:19]
	v_mfma_f32_16x16x32_bf16 v[4:7], v[148:151], v[214:217], v[4:7]
	v_mfma_f32_16x16x32_bf16 v[0:3], v[170:173], v[214:217], v[0:3]
	s_setprio 0
	s_barrier
	s_add_i32 s3, 0, 0x18000
	s_add_i32 s73, 0, 0x1c000
	v_add_u32_e32 v140, s3, v187
	v_add_u32_e32 v170, s73, v187
	ds_read_b128 v[128:131], v140
	ds_read_b128 v[132:135], v140 offset:1024
	ds_read_b128 v[136:139], v140 offset:2048
	ds_read_b128 v[140:143], v140 offset:3072
	ds_read_b128 v[144:147], v170
	ds_read_b128 v[148:151], v170 offset:1024
	ds_read_b128 v[166:169], v170 offset:2048
	ds_read_b128 v[170:173], v170 offset:3072
	s_add_u32 s38, s44, 0x158000
	s_addc_u32 s39, s45, 0
	s_mov_b32 m0, s51
	ds_read_b128 v[174:177], v190 offset:32768
	ds_read_b128 v[178:181], v190 offset:33792
	ds_read_b128 v[194:197], v190 offset:34816
	ds_read_b128 v[198:201], v190 offset:35840
	ds_read_b128 v[202:205], v190 offset:36864
	ds_read_b128 v[206:209], v190 offset:37888
	ds_read_b128 v[210:213], v190 offset:38912
	ds_read_b128 v[214:217], v190 offset:39936
	global_load_lds_dwordx4 v152, s[38:39]
	s_mov_b32 m0, s52
	s_nop 0
	global_load_lds_dwordx4 v156, s[38:39]
	s_waitcnt vmcnt(8)
	s_waitcnt lgkmcnt(0)
	s_setprio 1
	s_barrier
	v_mfma_f32_16x16x32_bf16 v[124:127], v[128:131], v[174:177], v[124:127]
	v_mfma_f32_16x16x32_bf16 v[120:123], v[136:139], v[174:177], v[120:123]
	v_mfma_f32_16x16x32_bf16 v[108:111], v[128:131], v[194:197], v[108:111]
	v_mfma_f32_16x16x32_bf16 v[104:107], v[136:139], v[194:197], v[104:107]
	v_mfma_f32_16x16x32_bf16 v[92:95], v[128:131], v[202:205], v[92:95]
	v_mfma_f32_16x16x32_bf16 v[88:91], v[136:139], v[202:205], v[88:91]
	v_mfma_f32_16x16x32_bf16 v[76:79], v[128:131], v[210:213], v[76:79]
	v_mfma_f32_16x16x32_bf16 v[72:75], v[136:139], v[210:213], v[72:75]
	v_mfma_f32_16x16x32_bf16 v[124:127], v[132:135], v[178:181], v[124:127]
	v_mfma_f32_16x16x32_bf16 v[120:123], v[140:143], v[178:181], v[120:123]
	v_mfma_f32_16x16x32_bf16 v[108:111], v[132:135], v[198:201], v[108:111]
	v_mfma_f32_16x16x32_bf16 v[104:107], v[140:143], v[198:201], v[104:107]
	v_mfma_f32_16x16x32_bf16 v[92:95], v[132:135], v[206:209], v[92:95]
	v_mfma_f32_16x16x32_bf16 v[88:91], v[140:143], v[206:209], v[88:91]
	v_mfma_f32_16x16x32_bf16 v[76:79], v[132:135], v[214:217], v[76:79]
	v_mfma_f32_16x16x32_bf16 v[72:75], v[140:143], v[214:217], v[72:75]
	s_setprio 0
	s_setprio 1
	v_mfma_f32_16x16x32_bf16 v[116:119], v[144:147], v[174:177], v[116:119]
	v_mfma_f32_16x16x32_bf16 v[112:115], v[166:169], v[174:177], v[112:115]
	v_mfma_f32_16x16x32_bf16 v[100:103], v[144:147], v[194:197], v[100:103]
	v_mfma_f32_16x16x32_bf16 v[96:99], v[166:169], v[194:197], v[96:99]
	v_mfma_f32_16x16x32_bf16 v[84:87], v[144:147], v[202:205], v[84:87]
	v_mfma_f32_16x16x32_bf16 v[80:83], v[166:169], v[202:205], v[80:83]
	v_mfma_f32_16x16x32_bf16 v[68:71], v[144:147], v[210:213], v[68:71]
	v_mfma_f32_16x16x32_bf16 v[64:67], v[166:169], v[210:213], v[64:67]
	v_mfma_f32_16x16x32_bf16 v[116:119], v[148:151], v[178:181], v[116:119]
	v_mfma_f32_16x16x32_bf16 v[112:115], v[170:173], v[178:181], v[112:115]
	v_mfma_f32_16x16x32_bf16 v[100:103], v[148:151], v[198:201], v[100:103]
	v_mfma_f32_16x16x32_bf16 v[96:99], v[170:173], v[198:201], v[96:99]
	v_mfma_f32_16x16x32_bf16 v[84:87], v[148:151], v[206:209], v[84:87]
	v_mfma_f32_16x16x32_bf16 v[80:83], v[170:173], v[206:209], v[80:83]
	v_mfma_f32_16x16x32_bf16 v[68:71], v[148:151], v[214:217], v[68:71]
	v_mfma_f32_16x16x32_bf16 v[64:67], v[170:173], v[214:217], v[64:67]
	s_setprio 0
	s_barrier
	s_add_i32 s3, s3, s33
	s_mov_b32 m0, s3
	ds_read_b128 v[174:177], v190 offset:49152
	ds_read_b128 v[178:181], v190 offset:50176
	ds_read_b128 v[194:197], v190 offset:51200
	ds_read_b128 v[198:201], v190 offset:52224
	ds_read_b128 v[202:205], v190 offset:53248
	ds_read_b128 v[206:209], v190 offset:54272
	ds_read_b128 v[210:213], v190 offset:55296
	ds_read_b128 v[214:217], v190 offset:56320
	global_load_lds_dwordx4 v154, s[98:99]
	s_add_i32 m0, s3, 0x2000
	s_add_u32 s38, s42, 0x158080
	s_addc_u32 s39, s43, 0
	s_add_i32 s3, s73, s33
	global_load_lds_dwordx4 v158, s[98:99]
	s_mov_b32 m0, s3
	s_nop 0
	global_load_lds_dwordx4 v154, s[38:39]
	s_add_i32 m0, s3, 0x2000
	s_nop 0
	global_load_lds_dwordx4 v158, s[38:39]
	s_mov_b32 m0, s56
	s_nop 0
	global_load_lds_dwordx4 v152, s[100:101]
	s_mov_b32 m0, s57
	s_nop 0
	global_load_lds_dwordx4 v156, s[100:101]
	s_nop 0
	s_waitcnt vmcnt(8)
	s_waitcnt lgkmcnt(0)
	s_setprio 1
	s_barrier
	v_mfma_f32_16x16x32_bf16 v[60:63], v[128:131], v[174:177], v[60:63]
	v_mfma_f32_16x16x32_bf16 v[56:59], v[136:139], v[174:177], v[56:59]
	v_mfma_f32_16x16x32_bf16 v[44:47], v[128:131], v[194:197], v[44:47]
	v_mfma_f32_16x16x32_bf16 v[40:43], v[136:139], v[194:197], v[40:43]
	v_mfma_f32_16x16x32_bf16 v[28:31], v[128:131], v[202:205], v[28:31]
	v_mfma_f32_16x16x32_bf16 v[24:27], v[136:139], v[202:205], v[24:27]
	v_mfma_f32_16x16x32_bf16 v[12:15], v[128:131], v[210:213], v[12:15]
	v_mfma_f32_16x16x32_bf16 v[8:11], v[136:139], v[210:213], v[8:11]
	v_mfma_f32_16x16x32_bf16 v[60:63], v[132:135], v[178:181], v[60:63]
	v_mfma_f32_16x16x32_bf16 v[56:59], v[140:143], v[178:181], v[56:59]
	v_mfma_f32_16x16x32_bf16 v[44:47], v[132:135], v[198:201], v[44:47]
	v_mfma_f32_16x16x32_bf16 v[40:43], v[140:143], v[198:201], v[40:43]
	v_mfma_f32_16x16x32_bf16 v[28:31], v[132:135], v[206:209], v[28:31]
	v_mfma_f32_16x16x32_bf16 v[24:27], v[140:143], v[206:209], v[24:27]
	v_mfma_f32_16x16x32_bf16 v[12:15], v[132:135], v[214:217], v[12:15]
	v_mfma_f32_16x16x32_bf16 v[8:11], v[140:143], v[214:217], v[8:11]
	s_setprio 0
	s_setprio 1
	v_mfma_f32_16x16x32_bf16 v[52:55], v[144:147], v[174:177], v[52:55]
	v_mfma_f32_16x16x32_bf16 v[48:51], v[166:169], v[174:177], v[48:51]
	v_mfma_f32_16x16x32_bf16 v[36:39], v[144:147], v[194:197], v[36:39]
	v_mfma_f32_16x16x32_bf16 v[32:35], v[166:169], v[194:197], v[32:35]
	v_mfma_f32_16x16x32_bf16 v[20:23], v[144:147], v[202:205], v[20:23]
	v_mfma_f32_16x16x32_bf16 v[16:19], v[166:169], v[202:205], v[16:19]
	v_mfma_f32_16x16x32_bf16 v[4:7], v[144:147], v[210:213], v[4:7]
	v_mfma_f32_16x16x32_bf16 v[0:3], v[166:169], v[210:213], v[0:3]
	v_mfma_f32_16x16x32_bf16 v[52:55], v[148:151], v[178:181], v[52:55]
	v_mfma_f32_16x16x32_bf16 v[48:51], v[170:173], v[178:181], v[48:51]
	v_mfma_f32_16x16x32_bf16 v[36:39], v[148:151], v[198:201], v[36:39]
	v_mfma_f32_16x16x32_bf16 v[32:35], v[170:173], v[198:201], v[32:35]
	v_mfma_f32_16x16x32_bf16 v[20:23], v[148:151], v[206:209], v[20:23]
	v_mfma_f32_16x16x32_bf16 v[16:19], v[170:173], v[206:209], v[16:19]
	v_mfma_f32_16x16x32_bf16 v[4:7], v[148:151], v[214:217], v[4:7]
	v_mfma_f32_16x16x32_bf16 v[0:3], v[170:173], v[214:217], v[0:3]
	s_setprio 0
	s_barrier
	s_add_i32 s1, s1, 2
	s_add_u32 s4, s4, 0x100
	s_addc_u32 s5, s5, 0
	s_cmpk_gt_u32 s1, 0x53
	s_mov_b64 s[38:39], s[40:41]
.LBB0_876:
	ds_read_b128 v[128:131], v188
	ds_read_b128 v[132:135], v188 offset:1024
	ds_read_b128 v[136:139], v188 offset:2048
	ds_read_b128 v[140:143], v188 offset:3072
	ds_read_b128 v[144:147], v189
	ds_read_b128 v[148:151], v189 offset:1024
	ds_read_b128 v[166:169], v189 offset:2048
	ds_read_b128 v[170:173], v189 offset:3072
	s_add_u32 s40, s38, 0x100
	s_addc_u32 s41, s39, 0
	s_cmpk_eq_i32 s1, 0x52
	s_cselect_b32 s45, s37, s41
	s_cselect_b32 s44, s36, s40
	s_cselect_b32 s43, s17, s5
	s_cselect_b32 s42, s16, s4
	s_add_i32 m0, s48, 0xc000
	ds_read_b128 v[174:177], v190
	ds_read_b128 v[178:181], v190 offset:1024
	ds_read_b128 v[194:197], v190 offset:2048
	ds_read_b128 v[198:201], v190 offset:3072
	ds_read_b128 v[202:205], v190 offset:4096
	ds_read_b128 v[206:209], v190 offset:5120
	ds_read_b128 v[210:213], v190 offset:6144
	ds_read_b128 v[214:217], v190 offset:7168
	global_load_lds_dwordx4 v160, s[38:39]
	s_add_i32 m0, s48, 0xe000
	s_nop 0
	global_load_lds_dwordx4 v162, s[38:39]
	s_nop 0
	s_waitcnt vmcnt(8)
	s_waitcnt lgkmcnt(0)
	s_setprio 1
	s_barrier
	v_mfma_f32_16x16x32_bf16 v[124:127], v[128:131], v[174:177], v[124:127]
	v_mfma_f32_16x16x32_bf16 v[120:123], v[136:139], v[174:177], v[120:123]
	v_mfma_f32_16x16x32_bf16 v[108:111], v[128:131], v[194:197], v[108:111]
	v_mfma_f32_16x16x32_bf16 v[104:107], v[136:139], v[194:197], v[104:107]
	v_mfma_f32_16x16x32_bf16 v[92:95], v[128:131], v[202:205], v[92:95]
	v_mfma_f32_16x16x32_bf16 v[88:91], v[136:139], v[202:205], v[88:91]
	v_mfma_f32_16x16x32_bf16 v[76:79], v[128:131], v[210:213], v[76:79]
	v_mfma_f32_16x16x32_bf16 v[72:75], v[136:139], v[210:213], v[72:75]
	v_mfma_f32_16x16x32_bf16 v[124:127], v[132:135], v[178:181], v[124:127]
	v_mfma_f32_16x16x32_bf16 v[120:123], v[140:143], v[178:181], v[120:123]
	v_mfma_f32_16x16x32_bf16 v[108:111], v[132:135], v[198:201], v[108:111]
	v_mfma_f32_16x16x32_bf16 v[104:107], v[140:143], v[198:201], v[104:107]
	v_mfma_f32_16x16x32_bf16 v[92:95], v[132:135], v[206:209], v[92:95]
	v_mfma_f32_16x16x32_bf16 v[88:91], v[140:143], v[206:209], v[88:91]
	v_mfma_f32_16x16x32_bf16 v[76:79], v[132:135], v[214:217], v[76:79]
	v_mfma_f32_16x16x32_bf16 v[72:75], v[140:143], v[214:217], v[72:75]
	s_setprio 0
	s_setprio 1
	v_mfma_f32_16x16x32_bf16 v[116:119], v[144:147], v[174:177], v[116:119]
	v_mfma_f32_16x16x32_bf16 v[112:115], v[166:169], v[174:177], v[112:115]
	v_mfma_f32_16x16x32_bf16 v[100:103], v[144:147], v[194:197], v[100:103]
	v_mfma_f32_16x16x32_bf16 v[96:99], v[166:169], v[194:197], v[96:99]
	v_mfma_f32_16x16x32_bf16 v[84:87], v[144:147], v[202:205], v[84:87]
	v_mfma_f32_16x16x32_bf16 v[80:83], v[166:169], v[202:205], v[80:83]
	v_mfma_f32_16x16x32_bf16 v[68:71], v[144:147], v[210:213], v[68:71]
	v_mfma_f32_16x16x32_bf16 v[64:67], v[166:169], v[210:213], v[64:67]
	v_mfma_f32_16x16x32_bf16 v[116:119], v[148:151], v[178:181], v[116:119]
	v_mfma_f32_16x16x32_bf16 v[112:115], v[170:173], v[178:181], v[112:115]
	v_mfma_f32_16x16x32_bf16 v[100:103], v[148:151], v[198:201], v[100:103]
	v_mfma_f32_16x16x32_bf16 v[96:99], v[170:173], v[198:201], v[96:99]
	v_mfma_f32_16x16x32_bf16 v[84:87], v[148:151], v[206:209], v[84:87]
	v_mfma_f32_16x16x32_bf16 v[80:83], v[170:173], v[206:209], v[80:83]
	v_mfma_f32_16x16x32_bf16 v[68:71], v[148:151], v[214:217], v[68:71]
	v_mfma_f32_16x16x32_bf16 v[64:67], v[170:173], v[214:217], v[64:67]
	s_setprio 0
	s_barrier
	s_add_i32 s3, s70, s33
	s_add_u32 s98, s42, s24
	s_addc_u32 s99, s43, s25
	s_mov_b32 m0, s3
	ds_read_b128 v[174:177], v190 offset:16384
	ds_read_b128 v[178:181], v190 offset:17408
	ds_read_b128 v[194:197], v190 offset:18432
	ds_read_b128 v[198:201], v190 offset:19456
	ds_read_b128 v[202:205], v190 offset:20480
	ds_read_b128 v[206:209], v190 offset:21504
	ds_read_b128 v[210:213], v190 offset:22528
	ds_read_b128 v[214:217], v190 offset:23552
	global_load_lds_dwordx4 v154, s[42:43]
	s_add_i32 m0, s3, 0x2000
	s_add_u32 s38, s42, 0x158000
	s_addc_u32 s39, s43, 0
	s_add_i32 s3, s71, s33
	global_load_lds_dwordx4 v158, s[42:43]
	s_mov_b32 m0, s3
	s_add_u32 s100, s44, s24
	s_addc_u32 s101, s45, s25
	global_load_lds_dwordx4 v154, s[38:39]
	s_add_i32 m0, s3, 0x2000
	s_nop 0
	global_load_lds_dwordx4 v158, s[38:39]
	s_mov_b32 m0, s48
	s_nop 0
	global_load_lds_dwordx4 v152, s[44:45]
	s_mov_b32 m0, s49
	s_nop 0
	global_load_lds_dwordx4 v156, s[44:45]
	s_waitcnt vmcnt(8)
	s_waitcnt lgkmcnt(0)
	s_setprio 1
	s_barrier
	v_mfma_f32_16x16x32_bf16 v[60:63], v[128:131], v[174:177], v[60:63]
	v_mfma_f32_16x16x32_bf16 v[56:59], v[136:139], v[174:177], v[56:59]
	v_mfma_f32_16x16x32_bf16 v[44:47], v[128:131], v[194:197], v[44:47]
	v_mfma_f32_16x16x32_bf16 v[40:43], v[136:139], v[194:197], v[40:43]
	v_mfma_f32_16x16x32_bf16 v[28:31], v[128:131], v[202:205], v[28:31]
	v_mfma_f32_16x16x32_bf16 v[24:27], v[136:139], v[202:205], v[24:27]
	v_mfma_f32_16x16x32_bf16 v[12:15], v[128:131], v[210:213], v[12:15]
	v_mfma_f32_16x16x32_bf16 v[8:11], v[136:139], v[210:213], v[8:11]
	v_mfma_f32_16x16x32_bf16 v[60:63], v[132:135], v[178:181], v[60:63]
	v_mfma_f32_16x16x32_bf16 v[56:59], v[140:143], v[178:181], v[56:59]
	v_mfma_f32_16x16x32_bf16 v[44:47], v[132:135], v[198:201], v[44:47]
	v_mfma_f32_16x16x32_bf16 v[40:43], v[140:143], v[198:201], v[40:43]
	v_mfma_f32_16x16x32_bf16 v[28:31], v[132:135], v[206:209], v[28:31]
	v_mfma_f32_16x16x32_bf16 v[24:27], v[140:143], v[206:209], v[24:27]
	v_mfma_f32_16x16x32_bf16 v[12:15], v[132:135], v[214:217], v[12:15]
	v_mfma_f32_16x16x32_bf16 v[8:11], v[140:143], v[214:217], v[8:11]
	s_setprio 0
	s_setprio 1
	v_mfma_f32_16x16x32_bf16 v[52:55], v[144:147], v[174:177], v[52:55]
	v_mfma_f32_16x16x32_bf16 v[48:51], v[166:169], v[174:177], v[48:51]
	v_mfma_f32_16x16x32_bf16 v[36:39], v[144:147], v[194:197], v[36:39]
	v_mfma_f32_16x16x32_bf16 v[32:35], v[166:169], v[194:197], v[32:35]
	v_mfma_f32_16x16x32_bf16 v[20:23], v[144:147], v[202:205], v[20:23]
	v_mfma_f32_16x16x32_bf16 v[16:19], v[166:169], v[202:205], v[16:19]
	v_mfma_f32_16x16x32_bf16 v[4:7], v[144:147], v[210:213], v[4:7]
	v_mfma_f32_16x16x32_bf16 v[0:3], v[166:169], v[210:213], v[0:3]
	v_mfma_f32_16x16x32_bf16 v[52:55], v[148:151], v[178:181], v[52:55]
	v_mfma_f32_16x16x32_bf16 v[48:51], v[170:173], v[178:181], v[48:51]
	v_mfma_f32_16x16x32_bf16 v[36:39], v[148:151], v[198:201], v[36:39]
	v_mfma_f32_16x16x32_bf16 v[32:35], v[170:173], v[198:201], v[32:35]
	v_mfma_f32_16x16x32_bf16 v[20:23], v[148:151], v[206:209], v[20:23]
	v_mfma_f32_16x16x32_bf16 v[16:19], v[170:173], v[206:209], v[16:19]
	v_mfma_f32_16x16x32_bf16 v[4:7], v[148:151], v[214:217], v[4:7]
	v_mfma_f32_16x16x32_bf16 v[0:3], v[170:173], v[214:217], v[0:3]
	s_setprio 0
	s_barrier
	s_add_i32 s3, 0, 0x18000
	s_add_i32 s73, 0, 0x1c000
	v_add_u32_e32 v140, s3, v187
	v_add_u32_e32 v170, s73, v187
	ds_read_b128 v[128:131], v140
	ds_read_b128 v[132:135], v140 offset:1024
	ds_read_b128 v[136:139], v140 offset:2048
	ds_read_b128 v[140:143], v140 offset:3072
	ds_read_b128 v[144:147], v170
	ds_read_b128 v[148:151], v170 offset:1024
	ds_read_b128 v[166:169], v170 offset:2048
	ds_read_b128 v[170:173], v170 offset:3072
	s_add_u32 s38, s44, 0x158000
	s_addc_u32 s39, s45, 0
	s_mov_b32 m0, s51
	ds_read_b128 v[174:177], v190 offset:32768
	ds_read_b128 v[178:181], v190 offset:33792
	ds_read_b128 v[194:197], v190 offset:34816
	ds_read_b128 v[198:201], v190 offset:35840
	ds_read_b128 v[202:205], v190 offset:36864
	ds_read_b128 v[206:209], v190 offset:37888
	ds_read_b128 v[210:213], v190 offset:38912
	ds_read_b128 v[214:217], v190 offset:39936
	global_load_lds_dwordx4 v152, s[38:39]
	s_mov_b32 m0, s52
	s_nop 0
	global_load_lds_dwordx4 v156, s[38:39]
	s_waitcnt vmcnt(8)
	s_waitcnt lgkmcnt(0)
	s_setprio 1
	s_barrier
	v_mfma_f32_16x16x32_bf16 v[124:127], v[128:131], v[174:177], v[124:127]
	v_mfma_f32_16x16x32_bf16 v[120:123], v[136:139], v[174:177], v[120:123]
	v_mfma_f32_16x16x32_bf16 v[108:111], v[128:131], v[194:197], v[108:111]
	v_mfma_f32_16x16x32_bf16 v[104:107], v[136:139], v[194:197], v[104:107]
	v_mfma_f32_16x16x32_bf16 v[92:95], v[128:131], v[202:205], v[92:95]
	v_mfma_f32_16x16x32_bf16 v[88:91], v[136:139], v[202:205], v[88:91]
	v_mfma_f32_16x16x32_bf16 v[76:79], v[128:131], v[210:213], v[76:79]
	v_mfma_f32_16x16x32_bf16 v[72:75], v[136:139], v[210:213], v[72:75]
	v_mfma_f32_16x16x32_bf16 v[124:127], v[132:135], v[178:181], v[124:127]
	v_mfma_f32_16x16x32_bf16 v[120:123], v[140:143], v[178:181], v[120:123]
	v_mfma_f32_16x16x32_bf16 v[108:111], v[132:135], v[198:201], v[108:111]
	v_mfma_f32_16x16x32_bf16 v[104:107], v[140:143], v[198:201], v[104:107]
	v_mfma_f32_16x16x32_bf16 v[92:95], v[132:135], v[206:209], v[92:95]
	v_mfma_f32_16x16x32_bf16 v[88:91], v[140:143], v[206:209], v[88:91]
	v_mfma_f32_16x16x32_bf16 v[76:79], v[132:135], v[214:217], v[76:79]
	v_mfma_f32_16x16x32_bf16 v[72:75], v[140:143], v[214:217], v[72:75]
	s_setprio 0
	s_setprio 1
	v_mfma_f32_16x16x32_bf16 v[116:119], v[144:147], v[174:177], v[116:119]
	v_mfma_f32_16x16x32_bf16 v[112:115], v[166:169], v[174:177], v[112:115]
	v_mfma_f32_16x16x32_bf16 v[100:103], v[144:147], v[194:197], v[100:103]
	v_mfma_f32_16x16x32_bf16 v[96:99], v[166:169], v[194:197], v[96:99]
	v_mfma_f32_16x16x32_bf16 v[84:87], v[144:147], v[202:205], v[84:87]
	v_mfma_f32_16x16x32_bf16 v[80:83], v[166:169], v[202:205], v[80:83]
	v_mfma_f32_16x16x32_bf16 v[68:71], v[144:147], v[210:213], v[68:71]
	v_mfma_f32_16x16x32_bf16 v[64:67], v[166:169], v[210:213], v[64:67]
	v_mfma_f32_16x16x32_bf16 v[116:119], v[148:151], v[178:181], v[116:119]
	v_mfma_f32_16x16x32_bf16 v[112:115], v[170:173], v[178:181], v[112:115]
	v_mfma_f32_16x16x32_bf16 v[100:103], v[148:151], v[198:201], v[100:103]
	v_mfma_f32_16x16x32_bf16 v[96:99], v[170:173], v[198:201], v[96:99]
	v_mfma_f32_16x16x32_bf16 v[84:87], v[148:151], v[206:209], v[84:87]
	v_mfma_f32_16x16x32_bf16 v[80:83], v[170:173], v[206:209], v[80:83]
	v_mfma_f32_16x16x32_bf16 v[68:71], v[148:151], v[214:217], v[68:71]
	v_mfma_f32_16x16x32_bf16 v[64:67], v[170:173], v[214:217], v[64:67]
	s_setprio 0
	s_barrier
	s_add_i32 s3, s3, s33
	s_mov_b32 m0, s3
	ds_read_b128 v[174:177], v190 offset:49152
	ds_read_b128 v[178:181], v190 offset:50176
	ds_read_b128 v[194:197], v190 offset:51200
	ds_read_b128 v[198:201], v190 offset:52224
	ds_read_b128 v[202:205], v190 offset:53248
	ds_read_b128 v[206:209], v190 offset:54272
	ds_read_b128 v[210:213], v190 offset:55296
	ds_read_b128 v[214:217], v190 offset:56320
	global_load_lds_dwordx4 v154, s[98:99]
	s_add_i32 m0, s3, 0x2000
	s_add_u32 s38, s42, 0x158080
	s_addc_u32 s39, s43, 0
	s_add_i32 s3, s73, s33
	global_load_lds_dwordx4 v158, s[98:99]
	s_mov_b32 m0, s3
	s_nop 0
	global_load_lds_dwordx4 v154, s[38:39]
	s_add_i32 m0, s3, 0x2000
	s_nop 0
	global_load_lds_dwordx4 v158, s[38:39]
	s_mov_b32 m0, s56
	s_nop 0
	global_load_lds_dwordx4 v152, s[100:101]
	s_mov_b32 m0, s57
	s_nop 0
	global_load_lds_dwordx4 v156, s[100:101]
	s_nop 0
	s_waitcnt vmcnt(8)
	s_waitcnt lgkmcnt(0)
	s_setprio 1
	s_barrier
	v_mfma_f32_16x16x32_bf16 v[60:63], v[128:131], v[174:177], v[60:63]
	v_mfma_f32_16x16x32_bf16 v[56:59], v[136:139], v[174:177], v[56:59]
	v_mfma_f32_16x16x32_bf16 v[44:47], v[128:131], v[194:197], v[44:47]
	v_mfma_f32_16x16x32_bf16 v[40:43], v[136:139], v[194:197], v[40:43]
	v_mfma_f32_16x16x32_bf16 v[28:31], v[128:131], v[202:205], v[28:31]
	v_mfma_f32_16x16x32_bf16 v[24:27], v[136:139], v[202:205], v[24:27]
	v_mfma_f32_16x16x32_bf16 v[12:15], v[128:131], v[210:213], v[12:15]
	v_mfma_f32_16x16x32_bf16 v[8:11], v[136:139], v[210:213], v[8:11]
	v_mfma_f32_16x16x32_bf16 v[60:63], v[132:135], v[178:181], v[60:63]
	v_mfma_f32_16x16x32_bf16 v[56:59], v[140:143], v[178:181], v[56:59]
	v_mfma_f32_16x16x32_bf16 v[44:47], v[132:135], v[198:201], v[44:47]
	v_mfma_f32_16x16x32_bf16 v[40:43], v[140:143], v[198:201], v[40:43]
	v_mfma_f32_16x16x32_bf16 v[28:31], v[132:135], v[206:209], v[28:31]
	v_mfma_f32_16x16x32_bf16 v[24:27], v[140:143], v[206:209], v[24:27]
	v_mfma_f32_16x16x32_bf16 v[12:15], v[132:135], v[214:217], v[12:15]
	v_mfma_f32_16x16x32_bf16 v[8:11], v[140:143], v[214:217], v[8:11]
	s_setprio 0
	s_setprio 1
	v_mfma_f32_16x16x32_bf16 v[52:55], v[144:147], v[174:177], v[52:55]
	v_mfma_f32_16x16x32_bf16 v[48:51], v[166:169], v[174:177], v[48:51]
	v_mfma_f32_16x16x32_bf16 v[36:39], v[144:147], v[194:197], v[36:39]
	v_mfma_f32_16x16x32_bf16 v[32:35], v[166:169], v[194:197], v[32:35]
	v_mfma_f32_16x16x32_bf16 v[20:23], v[144:147], v[202:205], v[20:23]
	v_mfma_f32_16x16x32_bf16 v[16:19], v[166:169], v[202:205], v[16:19]
	v_mfma_f32_16x16x32_bf16 v[4:7], v[144:147], v[210:213], v[4:7]
	v_mfma_f32_16x16x32_bf16 v[0:3], v[166:169], v[210:213], v[0:3]
	v_mfma_f32_16x16x32_bf16 v[52:55], v[148:151], v[178:181], v[52:55]
	v_mfma_f32_16x16x32_bf16 v[48:51], v[170:173], v[178:181], v[48:51]
	v_mfma_f32_16x16x32_bf16 v[36:39], v[148:151], v[198:201], v[36:39]
	v_mfma_f32_16x16x32_bf16 v[32:35], v[170:173], v[198:201], v[32:35]
	v_mfma_f32_16x16x32_bf16 v[20:23], v[148:151], v[206:209], v[20:23]
	v_mfma_f32_16x16x32_bf16 v[16:19], v[170:173], v[206:209], v[16:19]
	v_mfma_f32_16x16x32_bf16 v[4:7], v[148:151], v[214:217], v[4:7]
	v_mfma_f32_16x16x32_bf16 v[0:3], v[170:173], v[214:217], v[0:3]
	s_setprio 0
	s_barrier
	s_add_i32 s1, s1, 2
	s_add_u32 s4, s4, 0x100
	s_addc_u32 s5, s5, 0
	s_cmpk_gt_u32 s1, 0x53
	s_mov_b64 s[38:39], s[40:41]
	s_cbranch_scc0 .LBB0_876
	s_and_b64 vcc, exec, s[26:27]
	s_cbranch_vccz .LBB0_879
	s_barrier
